# baseline (speedup 1.0000x reference)
.LBB0_234:
	ds_read_b128 v[140:143], v138
	ds_read_b128 v[144:147], v138 offset:1024
	ds_read_b128 v[148:151], v138 offset:2048
	ds_read_b128 v[152:155], v138 offset:3072
	ds_read_b128 v[156:159], v193
	ds_read_b128 v[160:163], v193 offset:1024
	ds_read_b128 v[194:197], v192
	ds_read_b128 v[198:201], v192 offset:1024
	ds_read_b128 v[202:205], v191
	ds_read_b128 v[206:209], v191 offset:1024
	ds_read_b128 v[210:213], v190
	ds_read_b128 v[214:217], v190 offset:1024
	s_waitcnt lgkmcnt(8)
	s_waitcnt vmcnt(10)
	s_barrier
	s_waitcnt lgkmcnt(0)
	s_setprio 1
	s_waitcnt lgkmcnt(0)
	v_mfma_f32_16x16x32_bf16 v[124:127], v[140:143], v[156:159], v[124:127]
	v_mfma_f32_16x16x32_bf16 v[120:123], v[148:151], v[156:159], v[120:123]
	v_mfma_f32_16x16x32_bf16 v[116:119], v[140:143], v[194:197], v[116:119]
	v_mfma_f32_16x16x32_bf16 v[112:115], v[148:151], v[194:197], v[112:115]
	v_mfma_f32_16x16x32_bf16 v[108:111], v[140:143], v[202:205], v[108:111]
	v_mfma_f32_16x16x32_bf16 v[104:107], v[148:151], v[202:205], v[104:107]
	v_mfma_f32_16x16x32_bf16 v[100:103], v[140:143], v[210:213], v[100:103]
	v_mfma_f32_16x16x32_bf16 v[96:99], v[148:151], v[210:213], v[96:99]
	v_mfma_f32_16x16x32_bf16 v[124:127], v[144:147], v[160:163], v[124:127]
	v_mfma_f32_16x16x32_bf16 v[120:123], v[152:155], v[160:163], v[120:123]
	v_mfma_f32_16x16x32_bf16 v[116:119], v[144:147], v[198:201], v[116:119]
	v_mfma_f32_16x16x32_bf16 v[112:115], v[152:155], v[198:201], v[112:115]
	v_mfma_f32_16x16x32_bf16 v[108:111], v[144:147], v[206:209], v[108:111]
	v_mfma_f32_16x16x32_bf16 v[104:107], v[152:155], v[206:209], v[104:107]
	v_mfma_f32_16x16x32_bf16 v[100:103], v[144:147], v[214:217], v[100:103]
	v_mfma_f32_16x16x32_bf16 v[96:99], v[152:155], v[214:217], v[96:99]
	s_setprio 0
	s_barrier
	v_readfirstlane_b32 s82, v189
	v_lshl_add_u64 v[234:235], s[60:61], 0, v[164:165]
	s_mov_b32 m0, s82
	v_readfirstlane_b32 s82, v188
	ds_read_b128 v[218:221], v135
	ds_read_b128 v[222:225], v135 offset:1024
	ds_read_b128 v[226:229], v135 offset:2048
	ds_read_b128 v[230:233], v135 offset:3072
	global_load_lds_dwordx4 v[234:235], off
	v_lshl_add_u64 v[236:237], v[234:235], 0, s[2:3]
	s_mov_b32 m0, s82
	s_nop 0
	global_load_lds_dwordx4 v[236:237], off
	v_readfirstlane_b32 s82, v169
	v_lshl_add_u64 v[236:237], v[128:129], 0, s[22:23]
	s_mov_b32 m0, s82
	v_readfirstlane_b32 s82, v187
	global_load_lds_dwordx4 v[236:237], off
	v_lshl_add_u64 v[236:237], v[128:129], 0, s[24:25]
	s_mov_b32 m0, s82
	s_nop 0
	global_load_lds_dwordx4 v[236:237], off
	s_waitcnt vmcnt(12)
	s_barrier
	s_waitcnt lgkmcnt(0)
	s_setprio 1
	s_waitcnt lgkmcnt(0)
	v_mfma_f32_16x16x32_bf16 v[92:95], v[218:221], v[156:159], v[92:95]
	v_mfma_f32_16x16x32_bf16 v[88:91], v[226:229], v[156:159], v[88:91]
	v_mfma_f32_16x16x32_bf16 v[84:87], v[218:221], v[194:197], v[84:87]
	v_mfma_f32_16x16x32_bf16 v[80:83], v[226:229], v[194:197], v[80:83]
	v_mfma_f32_16x16x32_bf16 v[76:79], v[218:221], v[202:205], v[76:79]
	v_mfma_f32_16x16x32_bf16 v[72:75], v[226:229], v[202:205], v[72:75]
	v_mfma_f32_16x16x32_bf16 v[68:71], v[218:221], v[210:213], v[68:71]
	v_mfma_f32_16x16x32_bf16 v[64:67], v[226:229], v[210:213], v[64:67]
	v_mfma_f32_16x16x32_bf16 v[92:95], v[222:225], v[160:163], v[92:95]
	v_mfma_f32_16x16x32_bf16 v[88:91], v[230:233], v[160:163], v[88:91]
	v_mfma_f32_16x16x32_bf16 v[84:87], v[222:225], v[198:201], v[84:87]
	v_mfma_f32_16x16x32_bf16 v[80:83], v[230:233], v[198:201], v[80:83]
	v_mfma_f32_16x16x32_bf16 v[76:79], v[222:225], v[206:209], v[76:79]
	v_mfma_f32_16x16x32_bf16 v[72:75], v[230:233], v[206:209], v[72:75]
	v_mfma_f32_16x16x32_bf16 v[68:71], v[222:225], v[214:217], v[68:71]
	v_mfma_f32_16x16x32_bf16 v[64:67], v[230:233], v[214:217], v[64:67]
	s_setprio 0
	s_barrier
	ds_read_b128 v[156:159], v193 offset:16384
	ds_read_b128 v[160:163], v193 offset:17408
	ds_read_b128 v[194:197], v192 offset:16384
	ds_read_b128 v[198:201], v192 offset:17408
	ds_read_b128 v[202:205], v191 offset:16384
	ds_read_b128 v[206:209], v191 offset:17408
	ds_read_b128 v[210:213], v190 offset:16384
	ds_read_b128 v[214:217], v190 offset:17408
	v_readfirstlane_b32 s82, v186
	v_lshl_add_u64 v[236:237], v[234:235], 0, s[6:7]
	s_mov_b32 m0, s82
	v_readfirstlane_b32 s82, v185
	global_load_lds_dwordx4 v[236:237], off
	v_lshl_add_u64 v[236:237], v[234:235], 0, s[8:9]
	s_mov_b32 m0, s82
	s_nop 0
	global_load_lds_dwordx4 v[236:237], off
	s_barrier
	s_waitcnt lgkmcnt(0)
	s_setprio 1
	s_waitcnt lgkmcnt(0)
	v_mfma_f32_16x16x32_bf16 v[60:63], v[140:143], v[156:159], v[60:63]
	v_mfma_f32_16x16x32_bf16 v[56:59], v[148:151], v[156:159], v[56:59]
	v_mfma_f32_16x16x32_bf16 v[52:55], v[140:143], v[194:197], v[52:55]
	v_mfma_f32_16x16x32_bf16 v[48:51], v[148:151], v[194:197], v[48:51]
	v_mfma_f32_16x16x32_bf16 v[44:47], v[140:143], v[202:205], v[44:47]
	v_mfma_f32_16x16x32_bf16 v[40:43], v[148:151], v[202:205], v[40:43]
	v_mfma_f32_16x16x32_bf16 v[36:39], v[140:143], v[210:213], v[36:39]
	v_mfma_f32_16x16x32_bf16 v[32:35], v[148:151], v[210:213], v[32:35]
	v_mfma_f32_16x16x32_bf16 v[60:63], v[144:147], v[160:163], v[60:63]
	v_mfma_f32_16x16x32_bf16 v[56:59], v[152:155], v[160:163], v[56:59]
	v_mfma_f32_16x16x32_bf16 v[52:55], v[144:147], v[198:201], v[52:55]
	v_mfma_f32_16x16x32_bf16 v[48:51], v[152:155], v[198:201], v[48:51]
	v_mfma_f32_16x16x32_bf16 v[44:47], v[144:147], v[206:209], v[44:47]
	v_mfma_f32_16x16x32_bf16 v[40:43], v[152:155], v[206:209], v[40:43]
	v_mfma_f32_16x16x32_bf16 v[36:39], v[144:147], v[214:217], v[36:39]
	v_mfma_f32_16x16x32_bf16 v[32:35], v[152:155], v[214:217], v[32:35]
	s_setprio 0
	s_barrier
	v_readfirstlane_b32 s82, v184
	v_lshl_add_u64 v[142:143], v[128:129], 0, s[26:27]
	s_mov_b32 m0, s82
	v_readfirstlane_b32 s82, v183
	global_load_lds_dwordx4 v[142:143], off
	s_mov_b32 m0, s82
	s_nop 0
	global_load_lds_dwordx4 v[128:129], off
	s_waitcnt vmcnt(12)
	s_barrier
	s_setprio 1
	v_mfma_f32_16x16x32_bf16 v[28:31], v[218:221], v[156:159], v[28:31]
	v_mfma_f32_16x16x32_bf16 v[24:27], v[226:229], v[156:159], v[24:27]
	v_mfma_f32_16x16x32_bf16 v[20:23], v[218:221], v[194:197], v[20:23]
	v_mfma_f32_16x16x32_bf16 v[16:19], v[226:229], v[194:197], v[16:19]
	v_mfma_f32_16x16x32_bf16 v[12:15], v[218:221], v[202:205], v[12:15]
	v_mfma_f32_16x16x32_bf16 v[8:11], v[226:229], v[202:205], v[8:11]
	v_mfma_f32_16x16x32_bf16 v[4:7], v[218:221], v[210:213], v[4:7]
	v_mfma_f32_16x16x32_bf16 v[0:3], v[226:229], v[210:213], v[0:3]
	v_mfma_f32_16x16x32_bf16 v[28:31], v[222:225], v[160:163], v[28:31]
	v_mfma_f32_16x16x32_bf16 v[24:27], v[230:233], v[160:163], v[24:27]
	v_mfma_f32_16x16x32_bf16 v[20:23], v[222:225], v[198:201], v[20:23]
	v_mfma_f32_16x16x32_bf16 v[16:19], v[230:233], v[198:201], v[16:19]
	v_mfma_f32_16x16x32_bf16 v[12:15], v[222:225], v[206:209], v[12:15]
	v_mfma_f32_16x16x32_bf16 v[8:11], v[230:233], v[206:209], v[8:11]
	v_mfma_f32_16x16x32_bf16 v[4:7], v[222:225], v[214:217], v[4:7]
	v_mfma_f32_16x16x32_bf16 v[0:3], v[230:233], v[214:217], v[0:3]
	s_setprio 0
	s_barrier
	ds_read_b128 v[140:143], v130
	ds_read_b128 v[144:147], v130 offset:1024
	ds_read_b128 v[148:151], v130 offset:2048
	ds_read_b128 v[152:155], v130 offset:3072
	ds_read_b128 v[156:159], v193 offset:32768
	ds_read_b128 v[160:163], v193 offset:33792
	ds_read_b128 v[194:197], v192 offset:32768
	ds_read_b128 v[198:201], v192 offset:33792
	ds_read_b128 v[202:205], v191 offset:32768
	ds_read_b128 v[206:209], v191 offset:33792
	ds_read_b128 v[210:213], v190 offset:32768
	ds_read_b128 v[214:217], v190 offset:33792
	s_waitcnt lgkmcnt(8)
	s_waitcnt vmcnt(10)
	s_barrier
	s_waitcnt lgkmcnt(0)
	s_setprio 1
	s_waitcnt lgkmcnt(0)
	v_mfma_f32_16x16x32_bf16 v[124:127], v[140:143], v[156:159], v[124:127]
	v_mfma_f32_16x16x32_bf16 v[120:123], v[148:151], v[156:159], v[120:123]
	v_mfma_f32_16x16x32_bf16 v[116:119], v[140:143], v[194:197], v[116:119]
	v_mfma_f32_16x16x32_bf16 v[112:115], v[148:151], v[194:197], v[112:115]
	v_mfma_f32_16x16x32_bf16 v[108:111], v[140:143], v[202:205], v[108:111]
	v_mfma_f32_16x16x32_bf16 v[104:107], v[148:151], v[202:205], v[104:107]
	v_mfma_f32_16x16x32_bf16 v[100:103], v[140:143], v[210:213], v[100:103]
	v_mfma_f32_16x16x32_bf16 v[96:99], v[148:151], v[210:213], v[96:99]
	v_mfma_f32_16x16x32_bf16 v[124:127], v[144:147], v[160:163], v[124:127]
	v_mfma_f32_16x16x32_bf16 v[120:123], v[152:155], v[160:163], v[120:123]
	v_mfma_f32_16x16x32_bf16 v[116:119], v[144:147], v[198:201], v[116:119]
	v_mfma_f32_16x16x32_bf16 v[112:115], v[152:155], v[198:201], v[112:115]
	v_mfma_f32_16x16x32_bf16 v[108:111], v[144:147], v[206:209], v[108:111]
	v_mfma_f32_16x16x32_bf16 v[104:107], v[152:155], v[206:209], v[104:107]
	v_mfma_f32_16x16x32_bf16 v[100:103], v[144:147], v[214:217], v[100:103]
	v_mfma_f32_16x16x32_bf16 v[96:99], v[152:155], v[214:217], v[96:99]
	s_setprio 0
	s_barrier
	v_readfirstlane_b32 s82, v182
	v_lshl_add_u64 v[234:235], s[56:57], 0, v[164:165]
	s_mov_b32 m0, s82
	v_readfirstlane_b32 s82, v181
	ds_read_b128 v[218:221], v132
	ds_read_b128 v[222:225], v132 offset:1024
	ds_read_b128 v[226:229], v132 offset:2048
	ds_read_b128 v[230:233], v132 offset:3072
	global_load_lds_dwordx4 v[234:235], off
	v_lshl_add_u64 v[236:237], v[234:235], 0, s[2:3]
	s_mov_b32 m0, s82
	s_nop 0
	global_load_lds_dwordx4 v[236:237], off
	v_readfirstlane_b32 s82, v177
	v_lshl_add_u64 v[236:237], v[128:129], 0, s[28:29]
	s_mov_b32 m0, s82
	v_readfirstlane_b32 s82, v175
	global_load_lds_dwordx4 v[236:237], off
	v_lshl_add_u64 v[236:237], v[128:129], 0, s[30:31]
	s_mov_b32 m0, s82
	s_nop 0
	global_load_lds_dwordx4 v[236:237], off
	s_waitcnt vmcnt(12)
	s_barrier
	s_waitcnt lgkmcnt(0)
	s_setprio 1
	s_waitcnt lgkmcnt(0)
	v_mfma_f32_16x16x32_bf16 v[92:95], v[218:221], v[156:159], v[92:95]
	v_mfma_f32_16x16x32_bf16 v[88:91], v[226:229], v[156:159], v[88:91]
	v_mfma_f32_16x16x32_bf16 v[84:87], v[218:221], v[194:197], v[84:87]
	v_mfma_f32_16x16x32_bf16 v[80:83], v[226:229], v[194:197], v[80:83]
	v_mfma_f32_16x16x32_bf16 v[76:79], v[218:221], v[202:205], v[76:79]
	v_mfma_f32_16x16x32_bf16 v[72:75], v[226:229], v[202:205], v[72:75]
	v_mfma_f32_16x16x32_bf16 v[68:71], v[218:221], v[210:213], v[68:71]
	v_mfma_f32_16x16x32_bf16 v[64:67], v[226:229], v[210:213], v[64:67]
	v_mfma_f32_16x16x32_bf16 v[92:95], v[222:225], v[160:163], v[92:95]
	v_mfma_f32_16x16x32_bf16 v[88:91], v[230:233], v[160:163], v[88:91]
	v_mfma_f32_16x16x32_bf16 v[84:87], v[222:225], v[198:201], v[84:87]
	v_mfma_f32_16x16x32_bf16 v[80:83], v[230:233], v[198:201], v[80:83]
	v_mfma_f32_16x16x32_bf16 v[76:79], v[222:225], v[206:209], v[76:79]
	v_mfma_f32_16x16x32_bf16 v[72:75], v[230:233], v[206:209], v[72:75]
	v_mfma_f32_16x16x32_bf16 v[68:71], v[222:225], v[214:217], v[68:71]
	v_mfma_f32_16x16x32_bf16 v[64:67], v[230:233], v[214:217], v[64:67]
	s_setprio 0
	s_barrier
	ds_read_b128 v[156:159], v193 offset:49152
	ds_read_b128 v[160:163], v193 offset:50176
	ds_read_b128 v[194:197], v192 offset:49152
	ds_read_b128 v[198:201], v192 offset:50176
	ds_read_b128 v[202:205], v191 offset:49152
	ds_read_b128 v[206:209], v191 offset:50176
	ds_read_b128 v[210:213], v190 offset:49152
	ds_read_b128 v[214:217], v190 offset:50176
	v_readfirstlane_b32 s82, v173
	v_lshl_add_u64 v[236:237], v[234:235], 0, s[6:7]
	s_mov_b32 m0, s82
	v_readfirstlane_b32 s82, v171
	global_load_lds_dwordx4 v[236:237], off
	v_lshl_add_u64 v[236:237], v[234:235], 0, s[8:9]
	s_mov_b32 m0, s82
	s_nop 0
	global_load_lds_dwordx4 v[236:237], off
	s_barrier
	s_waitcnt lgkmcnt(0)
	s_setprio 1
	s_waitcnt lgkmcnt(0)
	v_mfma_f32_16x16x32_bf16 v[60:63], v[140:143], v[156:159], v[60:63]
	v_mfma_f32_16x16x32_bf16 v[56:59], v[148:151], v[156:159], v[56:59]
	v_mfma_f32_16x16x32_bf16 v[52:55], v[140:143], v[194:197], v[52:55]
	v_mfma_f32_16x16x32_bf16 v[48:51], v[148:151], v[194:197], v[48:51]
	v_mfma_f32_16x16x32_bf16 v[44:47], v[140:143], v[202:205], v[44:47]
	v_mfma_f32_16x16x32_bf16 v[40:43], v[148:151], v[202:205], v[40:43]
	v_mfma_f32_16x16x32_bf16 v[36:39], v[140:143], v[210:213], v[36:39]
	v_mfma_f32_16x16x32_bf16 v[32:35], v[148:151], v[210:213], v[32:35]
	v_mfma_f32_16x16x32_bf16 v[60:63], v[144:147], v[160:163], v[60:63]
	v_mfma_f32_16x16x32_bf16 v[56:59], v[152:155], v[160:163], v[56:59]
	v_mfma_f32_16x16x32_bf16 v[52:55], v[144:147], v[198:201], v[52:55]
	v_mfma_f32_16x16x32_bf16 v[48:51], v[152:155], v[198:201], v[48:51]
	v_mfma_f32_16x16x32_bf16 v[44:47], v[144:147], v[206:209], v[44:47]
	v_mfma_f32_16x16x32_bf16 v[40:43], v[152:155], v[206:209], v[40:43]
	v_mfma_f32_16x16x32_bf16 v[36:39], v[144:147], v[214:217], v[36:39]
	v_mfma_f32_16x16x32_bf16 v[32:35], v[152:155], v[214:217], v[32:35]
	s_setprio 0
	s_barrier
	v_lshl_add_u64 v[128:129], v[128:129], 0, s[34:35]
	v_readfirstlane_b32 s82, v137
	v_lshl_add_u64 v[142:143], v[128:129], 0, s[18:19]
	s_mov_b32 m0, s82
	v_readfirstlane_b32 s82, v136
	global_load_lds_dwordx4 v[142:143], off
	v_lshl_add_u64 v[142:143], v[128:129], 0, s[20:21]
	s_mov_b32 m0, s82
	s_nop 0
	global_load_lds_dwordx4 v[142:143], off
	s_waitcnt vmcnt(12)
	s_barrier
	s_setprio 1
	v_mfma_f32_16x16x32_bf16 v[28:31], v[218:221], v[156:159], v[28:31]
	v_mfma_f32_16x16x32_bf16 v[24:27], v[226:229], v[156:159], v[24:27]
	v_mfma_f32_16x16x32_bf16 v[20:23], v[218:221], v[194:197], v[20:23]
	v_mfma_f32_16x16x32_bf16 v[16:19], v[226:229], v[194:197], v[16:19]
	v_mfma_f32_16x16x32_bf16 v[12:15], v[218:221], v[202:205], v[12:15]
	v_mfma_f32_16x16x32_bf16 v[8:11], v[226:229], v[202:205], v[8:11]
	v_mfma_f32_16x16x32_bf16 v[4:7], v[218:221], v[210:213], v[4:7]
	v_mfma_f32_16x16x32_bf16 v[0:3], v[226:229], v[210:213], v[0:3]
	v_mfma_f32_16x16x32_bf16 v[28:31], v[222:225], v[160:163], v[28:31]
	v_mfma_f32_16x16x32_bf16 v[24:27], v[230:233], v[160:163], v[24:27]
	v_mfma_f32_16x16x32_bf16 v[20:23], v[222:225], v[198:201], v[20:23]
	v_mfma_f32_16x16x32_bf16 v[16:19], v[230:233], v[198:201], v[16:19]
	v_mfma_f32_16x16x32_bf16 v[12:15], v[222:225], v[206:209], v[12:15]
	v_mfma_f32_16x16x32_bf16 v[8:11], v[230:233], v[206:209], v[8:11]
	v_mfma_f32_16x16x32_bf16 v[4:7], v[222:225], v[214:217], v[4:7]
	v_mfma_f32_16x16x32_bf16 v[0:3], v[230:233], v[214:217], v[0:3]
	s_setprio 0
	s_add_i32 s14, s14, 2
	s_add_u32 s56, s56, s58
	s_addc_u32 s57, s57, s59
	s_add_u32 s60, s60, s58
	s_addc_u32 s61, s61, s59
	s_cmp_lt_u32 s14, 28
	s_barrier
	s_cbranch_scc1 .LBB0_234
	s_lshl_b32 s14, s62, 3
	s_or_b32 s82, s63, s14
	s_lshl_b32 s56, s82, 8
	v_lshlrev_b32_e32 v128, 3, v131
	v_lshlrev_b32_e32 v129, 5, v131
	s_or_b32 s14, s56, 0x80
	v_and_b32_e32 v128, 0x7fff0, v128
	v_and_b32_e32 v129, 32, v129
	s_lshl_b64 s[58:59], s[14:15], 13
	v_add_u32_e32 v129, v129, v134
	v_add_lshl_u32 v128, v133, v128, 13
	s_add_u32 s58, s40, s58
	v_lshl_add_u32 v164, v129, 1, v128
	s_addc_u32 s59, s41, s59
	v_lshl_add_u64 v[128:129], s[58:59], 0, v[164:165]
	v_readfirstlane_b32 s14, v137
	ds_read_b128 v[140:143], v138
	ds_read_b128 v[144:147], v138 offset:1024
	ds_read_b128 v[148:151], v138 offset:2048
	ds_read_b128 v[152:155], v138 offset:3072
	ds_read_b128 v[156:159], v193
	ds_read_b128 v[160:163], v193 offset:1024
	ds_read_b128 v[194:197], v192
	ds_read_b128 v[198:201], v192 offset:1024
	ds_read_b128 v[202:205], v191
	ds_read_b128 v[206:209], v191 offset:1024
	ds_read_b128 v[210:213], v190
	ds_read_b128 v[214:217], v190 offset:1024
	v_lshl_add_u64 v[138:139], v[128:129], 0, s[44:45]
	s_mov_b32 m0, s14
	v_readfirstlane_b32 s14, v136
	global_load_lds_dwordx4 v[138:139], off
	v_lshl_add_u64 v[128:129], v[128:129], 0, s[46:47]
	s_mov_b32 m0, s14
	s_mov_b32 s57, s15
	global_load_lds_dwordx4 v[128:129], off
	s_mul_i32 s98, s78, s84
	s_add_i32 s98, s98, s33
	s_cmpk_lt_u32 s98, 0x400
	s_cbranch_scc0 .Lpf5_skip
	v_mbcnt_lo_u32_b32 v243, -1, 0
	v_mbcnt_hi_u32_b32 v243, -1, v243
	v_add_u32_e32 v243, s64, v243
	v_lshrrev_b32_e32 v244, 1, v243
	v_lshlrev_b32_e32 v244, 13, v244
	v_and_b32_e32 v245, 1, v243
	v_lshl_or_b32 v244, v245, 7, v244
	v_lshrrev_b32_e32 v245, 7, v243
	v_lshlrev_b32_e32 v245, 19, v245
	v_and_b32_e32 v246, 0x7f, v243
	v_lshl_or_b32 v245, v246, 7, v245
	s_lshr_b32 s99, s98, 8
	s_lshl_b32 s99, s99, 11
	s_lshl_b32 s100, s98, 8
	s_and_b32 s100, s100, 0x700
	s_or_b32 s99, s99, s100
	s_lshl_b32 s99, s99, 13
	s_add_u32 s100, s40, s99
	s_addc_u32 s101, s41, 0
	global_load_dword v246, v244, s[100:101]
	s_and_b32 s98, s98, 0xf8
	s_lshl_b32 s98, s98, 11
	s_add_u32 s100, s65, s98
	s_addc_u32 s101, s66, 0
	global_load_dword v247, v245, s[100:101]
.Lpf5_skip:
	s_waitcnt vmcnt(12)
	s_barrier
	s_waitcnt lgkmcnt(0)
	s_setprio 1
	s_waitcnt lgkmcnt(0)
	v_mfma_f32_16x16x32_bf16 v[124:127], v[140:143], v[156:159], v[124:127]
	v_mfma_f32_16x16x32_bf16 v[120:123], v[148:151], v[156:159], v[120:123]
	v_mfma_f32_16x16x32_bf16 v[116:119], v[140:143], v[194:197], v[116:119]
	v_mfma_f32_16x16x32_bf16 v[112:115], v[148:151], v[194:197], v[112:115]
	v_mfma_f32_16x16x32_bf16 v[108:111], v[140:143], v[202:205], v[108:111]
	v_mfma_f32_16x16x32_bf16 v[104:107], v[148:151], v[202:205], v[104:107]
	v_mfma_f32_16x16x32_bf16 v[100:103], v[140:143], v[210:213], v[100:103]
	v_mfma_f32_16x16x32_bf16 v[96:99], v[148:151], v[210:213], v[96:99]
	v_mfma_f32_16x16x32_bf16 v[124:127], v[144:147], v[160:163], v[124:127]
	v_mfma_f32_16x16x32_bf16 v[120:123], v[152:155], v[160:163], v[120:123]
	v_mfma_f32_16x16x32_bf16 v[116:119], v[144:147], v[198:201], v[116:119]
	v_mfma_f32_16x16x32_bf16 v[112:115], v[152:155], v[198:201], v[112:115]
	v_mfma_f32_16x16x32_bf16 v[108:111], v[144:147], v[206:209], v[108:111]
	v_mfma_f32_16x16x32_bf16 v[104:107], v[152:155], v[206:209], v[104:107]
	v_mfma_f32_16x16x32_bf16 v[100:103], v[144:147], v[214:217], v[100:103]
	v_mfma_f32_16x16x32_bf16 v[96:99], v[152:155], v[214:217], v[96:99]
	s_setprio 0
	s_barrier
	ds_read_b128 v[136:139], v135
	ds_read_b128 v[218:221], v135 offset:1024
	ds_read_b128 v[222:225], v135 offset:2048
	ds_read_b128 v[226:229], v135 offset:3072
	s_barrier
	s_waitcnt lgkmcnt(0)
	s_setprio 1
	s_waitcnt lgkmcnt(0)
	v_mfma_f32_16x16x32_bf16 v[92:95], v[136:139], v[156:159], v[92:95]
	v_mfma_f32_16x16x32_bf16 v[84:87], v[136:139], v[194:197], v[84:87]
	v_mfma_f32_16x16x32_bf16 v[80:83], v[222:225], v[194:197], v[80:83]
	v_mfma_f32_16x16x32_bf16 v[88:91], v[222:225], v[156:159], v[88:91]
	v_mfma_f32_16x16x32_bf16 v[76:79], v[136:139], v[202:205], v[76:79]
	v_mfma_f32_16x16x32_bf16 v[72:75], v[222:225], v[202:205], v[72:75]
	v_mfma_f32_16x16x32_bf16 v[68:71], v[136:139], v[210:213], v[68:71]
	v_mfma_f32_16x16x32_bf16 v[64:67], v[222:225], v[210:213], v[64:67]
	v_mfma_f32_16x16x32_bf16 v[156:159], v[218:221], v[160:163], v[92:95]
	v_mfma_f32_16x16x32_bf16 v[194:197], v[218:221], v[198:201], v[84:87]
	v_mfma_f32_16x16x32_bf16 v[198:201], v[226:229], v[198:201], v[80:83]
	v_mfma_f32_16x16x32_bf16 v[160:163], v[226:229], v[160:163], v[88:91]
	v_mfma_f32_16x16x32_bf16 v[202:205], v[218:221], v[206:209], v[76:79]
	v_mfma_f32_16x16x32_bf16 v[206:209], v[226:229], v[206:209], v[72:75]
	v_mfma_f32_16x16x32_bf16 v[210:213], v[218:221], v[214:217], v[68:71]
	v_mfma_f32_16x16x32_bf16 v[214:217], v[226:229], v[214:217], v[64:67]
	s_setprio 0
	s_barrier
	s_nop 0
	ds_read_b128 v[64:67], v193 offset:16384
	ds_read_b128 v[68:71], v193 offset:17408
	ds_read_b128 v[72:75], v192 offset:16384
	ds_read_b128 v[76:79], v192 offset:17408
	ds_read_b128 v[80:83], v191 offset:16384
	ds_read_b128 v[84:87], v191 offset:17408
	ds_read_b128 v[88:91], v190 offset:16384
	ds_read_b128 v[92:95], v190 offset:17408
	s_waitcnt vmcnt(6)
	s_barrier
	s_waitcnt lgkmcnt(0)
	s_setprio 1
	s_waitcnt lgkmcnt(0)
	v_mfma_f32_16x16x32_bf16 v[60:63], v[140:143], v[64:67], v[60:63]
	v_mfma_f32_16x16x32_bf16 v[56:59], v[148:151], v[64:67], v[56:59]
	v_mfma_f32_16x16x32_bf16 v[52:55], v[140:143], v[72:75], v[52:55]
	v_mfma_f32_16x16x32_bf16 v[48:51], v[148:151], v[72:75], v[48:51]
	v_mfma_f32_16x16x32_bf16 v[230:233], v[140:143], v[80:83], v[44:47]
	v_mfma_f32_16x16x32_bf16 v[234:237], v[148:151], v[80:83], v[40:43]
	v_mfma_f32_16x16x32_bf16 v[140:143], v[140:143], v[88:91], v[36:39]
	v_mfma_f32_16x16x32_bf16 v[148:151], v[148:151], v[88:91], v[32:35]
	v_mfma_f32_16x16x32_bf16 v[32:35], v[144:147], v[68:71], v[60:63]
	v_mfma_f32_16x16x32_bf16 v[36:39], v[152:155], v[68:71], v[56:59]
	v_mfma_f32_16x16x32_bf16 v[40:43], v[144:147], v[76:79], v[52:55]
	v_mfma_f32_16x16x32_bf16 v[44:47], v[152:155], v[76:79], v[48:51]
	v_mfma_f32_16x16x32_bf16 v[48:51], v[144:147], v[84:87], v[230:233]
	v_mfma_f32_16x16x32_bf16 v[52:55], v[152:155], v[84:87], v[234:237]
	v_mfma_f32_16x16x32_bf16 v[56:59], v[144:147], v[92:95], v[140:143]
	v_mfma_f32_16x16x32_bf16 v[60:63], v[152:155], v[92:95], v[148:151]
	s_setprio 0
	s_setprio 1
	v_mfma_f32_16x16x32_bf16 v[28:31], v[136:139], v[64:67], v[28:31]
	v_mfma_f32_16x16x32_bf16 v[24:27], v[222:225], v[64:67], v[24:27]
	v_mfma_f32_16x16x32_bf16 v[20:23], v[136:139], v[72:75], v[20:23]
	v_mfma_f32_16x16x32_bf16 v[64:67], v[222:225], v[72:75], v[16:19]
	v_mfma_f32_16x16x32_bf16 v[12:15], v[136:139], v[80:83], v[12:15]
	v_mfma_f32_16x16x32_bf16 v[8:11], v[222:225], v[80:83], v[8:11]
	v_mfma_f32_16x16x32_bf16 v[72:75], v[136:139], v[88:91], v[4:7]
	v_mfma_f32_16x16x32_bf16 v[80:83], v[222:225], v[88:91], v[0:3]
	v_mfma_f32_16x16x32_bf16 v[0:3], v[218:221], v[68:71], v[28:31]
	v_mfma_f32_16x16x32_bf16 v[4:7], v[226:229], v[68:71], v[24:27]
	v_mfma_f32_16x16x32_bf16 v[16:19], v[218:221], v[76:79], v[20:23]
	v_mfma_f32_16x16x32_bf16 v[20:23], v[226:229], v[76:79], v[64:67]
	v_mfma_f32_16x16x32_bf16 v[24:27], v[218:221], v[84:87], v[12:15]
	v_mfma_f32_16x16x32_bf16 v[28:31], v[226:229], v[84:87], v[8:11]
	v_mfma_f32_16x16x32_bf16 v[64:67], v[218:221], v[92:95], v[72:75]
	v_mfma_f32_16x16x32_bf16 v[68:71], v[226:229], v[92:95], v[80:83]
	s_setprio 0
	s_barrier
	ds_read_b128 v[12:15], v130
	ds_read_b128 v[8:11], v130 offset:1024
	ds_read_b128 v[76:79], v130 offset:2048
	ds_read_b128 v[72:75], v130 offset:3072
	ds_read_b128 v[140:143], v193 offset:32768
	ds_read_b128 v[148:151], v193 offset:33792
	ds_read_b128 v[218:221], v192 offset:32768
	ds_read_b128 v[222:225], v192 offset:33792
	ds_read_b128 v[226:229], v191 offset:32768
	ds_read_b128 v[230:233], v191 offset:33792
	ds_read_b128 v[234:237], v190 offset:32768
	ds_read_b128 v[238:241], v190 offset:33792
	s_waitcnt vmcnt(4)
	s_barrier
	s_waitcnt lgkmcnt(0)
	s_setprio 1
	s_waitcnt lgkmcnt(0)
	v_mfma_f32_16x16x32_bf16 v[80:83], v[12:15], v[140:143], v[124:127]
	v_mfma_f32_16x16x32_bf16 v[84:87], v[76:79], v[140:143], v[120:123]
	v_mfma_f32_16x16x32_bf16 v[88:91], v[12:15], v[218:221], v[116:119]
	v_mfma_f32_16x16x32_bf16 v[92:95], v[76:79], v[218:221], v[112:115]
	v_mfma_f32_16x16x32_bf16 v[108:111], v[12:15], v[226:229], v[108:111]
	v_mfma_f32_16x16x32_bf16 v[104:107], v[76:79], v[226:229], v[104:107]
	v_mfma_f32_16x16x32_bf16 v[100:103], v[12:15], v[234:237], v[100:103]
	v_mfma_f32_16x16x32_bf16 v[96:99], v[76:79], v[234:237], v[96:99]
	v_mfma_f32_16x16x32_bf16 v[152:155], v[8:11], v[148:151], v[80:83]
	v_mfma_f32_16x16x32_bf16 v[144:147], v[72:75], v[148:151], v[84:87]
	v_mfma_f32_16x16x32_bf16 v[136:139], v[8:11], v[222:225], v[88:91]
	v_mfma_f32_16x16x32_bf16 v[128:131], v[72:75], v[222:225], v[92:95]
	v_mfma_f32_16x16x32_bf16 v[120:123], v[8:11], v[230:233], v[108:111]
	v_mfma_f32_16x16x32_bf16 v[112:115], v[72:75], v[230:233], v[104:107]
	v_mfma_f32_16x16x32_bf16 v[104:107], v[8:11], v[238:241], v[100:103]
	v_mfma_f32_16x16x32_bf16 v[96:99], v[72:75], v[238:241], v[96:99]
	s_setprio 0
	s_barrier
	ds_read_b128 v[88:91], v132
	ds_read_b128 v[80:83], v132 offset:1024
	ds_read_b128 v[92:95], v132 offset:2048
	ds_read_b128 v[84:87], v132 offset:3072
	s_waitcnt vmcnt(2)
	s_barrier
	s_waitcnt lgkmcnt(0)
	s_setprio 1
	s_waitcnt lgkmcnt(0)
	v_mfma_f32_16x16x32_bf16 v[100:103], v[88:91], v[140:143], v[156:159]
	v_mfma_f32_16x16x32_bf16 v[108:111], v[92:95], v[140:143], v[160:163]
	v_mfma_f32_16x16x32_bf16 v[116:119], v[88:91], v[218:221], v[194:197]
	v_mfma_f32_16x16x32_bf16 v[124:127], v[92:95], v[218:221], v[198:201]
	v_mfma_f32_16x16x32_bf16 v[160:163], v[88:91], v[226:229], v[202:205]
	v_mfma_f32_16x16x32_bf16 v[194:197], v[92:95], v[226:229], v[206:209]
	v_mfma_f32_16x16x32_bf16 v[198:201], v[88:91], v[234:237], v[210:213]
	v_mfma_f32_16x16x32_bf16 v[202:205], v[92:95], v[234:237], v[214:217]
	v_mfma_f32_16x16x32_bf16 v[156:159], v[80:83], v[148:151], v[100:103]
	v_mfma_f32_16x16x32_bf16 v[148:151], v[84:87], v[148:151], v[108:111]
	v_mfma_f32_16x16x32_bf16 v[140:143], v[80:83], v[222:225], v[116:119]
	v_mfma_f32_16x16x32_bf16 v[132:135], v[84:87], v[222:225], v[124:127]
	v_mfma_f32_16x16x32_bf16 v[124:127], v[80:83], v[230:233], v[160:163]
	v_mfma_f32_16x16x32_bf16 v[116:119], v[84:87], v[230:233], v[194:197]
	v_mfma_f32_16x16x32_bf16 v[108:111], v[80:83], v[238:241], v[198:201]
	v_mfma_f32_16x16x32_bf16 v[100:103], v[84:87], v[238:241], v[202:205]
	s_setprio 0
	s_lshl_b64 s[58:59], s[56:57], 2
	s_barrier
	v_mbcnt_lo_u32_b32 v162, -1, 0
	v_mbcnt_hi_u32_b32 v162, -1, v162
	s_add_u32 s58, s87, s58
	v_add_u32_e32 v160, s64, v162
	s_addc_u32 s59, s88, s59
	v_and_b32_e32 v164, 0x100, v160
	v_and_b32_e32 v162, 15, v162
	v_lshl_add_u64 v[160:161], s[58:59], 0, v[164:165]
	v_lshlrev_b32_e32 v164, 2, v162
	v_lshl_add_u64 v[160:161], v[160:161], 0, v[164:165]
	global_load_dword v180, v[160:161], off
	global_load_dword v178, v[160:161], off offset:64
	global_load_dword v176, v[160:161], off offset:128
	global_load_dword v174, v[160:161], off offset:192
	global_load_dword v172, v[160:161], off offset:512
	global_load_dword v170, v[160:161], off offset:576
	global_load_dword v168, v[160:161], off offset:640
	global_load_dword v166, v[160:161], off offset:704
	v_mbcnt_lo_u32_b32 v194, -1, 0
	v_mbcnt_hi_u32_b32 v194, -1, v194
	s_cmp_lg_u32 s81, 0
	v_add_u32_e32 v160, s64, v194
	v_bfe_u32 v196, v160, 8, 1
	v_ashrrev_i32_e32 v199, 6, v160
	v_bfe_u32 v160, v194, 4, 2
	s_cselect_b64 s[58:59], -1, 0
	v_and_b32_e32 v197, 3, v199
	v_and_b32_e32 v195, 15, v194
	s_and_b64 vcc, exec, s[58:59]
	v_lshlrev_b32_e32 v198, 4, v160
	s_cbranch_vccz .LBB0_246
	s_lshl_b32 s14, s80, 22
	s_lshl_b32 s57, s82, 14
	s_add_i32 s57, s57, s14
	v_lshlrev_b32_e32 v160, 6, v195
	v_or3_b32 v160, s57, v160, v198
	v_lshl_add_u32 v160, v197, 20, v160
	v_lshl_or_b32 v164, v196, 12, v160
	s_waitcnt vmcnt(0)
	v_pk_mul_f32 v[160:161], v[154:155], v[180:181] op_sel_hi:[1,0]
	v_pk_mul_f32 v[200:201], v[146:147], v[180:181] op_sel_hi:[1,0]
	v_max_f32_e32 v160, 0, v160
	v_mul_f32_e32 v204, v160, v160
	v_max_f32_e32 v160, 0, v200
	v_pk_mul_f32 v[162:163], v[152:153], v[180:181] op_sel_hi:[1,0]
	v_mul_f32_e32 v200, v160, v160
	v_max_f32_e32 v160, 0, v161
	v_pk_mul_f32 v[202:203], v[144:145], v[180:181] op_sel_hi:[1,0]
	v_max_f32_e32 v162, 0, v162
	v_max_f32_e32 v163, 0, v163
	v_mul_f32_e32 v161, v160, v160
	v_max_f32_e32 v160, 0, v201
	v_mul_f32_e32 v162, v162, v162
	v_max_f32_e32 v202, 0, v202
	v_mul_f32_e32 v163, v163, v163
	v_max_f32_e32 v203, 0, v203
	v_mul_f32_e32 v201, v160, v160
	v_cvt_pk_bf16_f32 v160, v162, v163
	v_cvt_pk_bf16_f32 v161, v204, v161
	v_mul_f32_e32 v202, v202, v202
	v_mul_f32_e32 v203, v203, v203
	v_cvt_pk_bf16_f32 v162, v202, v203
	v_cvt_pk_bf16_f32 v163, v200, v201
	global_store_dwordx4 v164, v[160:163], s[0:1]
	v_pk_mul_f32 v[202:203], v[150:151], v[180:181] op_sel_hi:[1,0]
	v_lshl_add_u64 v[200:201], s[0:1], 0, v[164:165]
	v_pk_mul_f32 v[160:161], v[158:159], v[180:181] op_sel_hi:[1,0]
	v_pk_mul_f32 v[162:163], v[156:157], v[180:181] op_sel_hi:[1,0]
	v_max_f32_e32 v160, 0, v160
	v_mul_f32_e32 v206, v160, v160
	v_max_f32_e32 v160, 0, v202
	v_mul_f32_e32 v202, v160, v160
	v_max_f32_e32 v160, 0, v161
	v_pk_mul_f32 v[204:205], v[148:149], v[180:181] op_sel_hi:[1,0]
	v_max_f32_e32 v162, 0, v162
	v_max_f32_e32 v163, 0, v163
	v_mul_f32_e32 v161, v160, v160
	v_max_f32_e32 v160, 0, v203
	v_add_co_u32_e32 v200, vcc, s74, v200
	v_mul_f32_e32 v162, v162, v162
	v_max_f32_e32 v204, 0, v204
	v_mul_f32_e32 v163, v163, v163
	v_max_f32_e32 v205, 0, v205
	v_mul_f32_e32 v203, v160, v160
	v_cvt_pk_bf16_f32 v160, v162, v163
	v_cvt_pk_bf16_f32 v161, v206, v161
	v_addc_co_u32_e32 v201, vcc, 0, v201, vcc
	v_mul_f32_e32 v204, v204, v204
	v_mul_f32_e32 v205, v205, v205
	v_cvt_pk_bf16_f32 v162, v204, v205
	v_cvt_pk_bf16_f32 v163, v202, v203
	global_store_dwordx4 v[200:201], v[160:163], off
	v_pk_mul_f32 v[202:203], v[130:131], v[178:179] op_sel_hi:[1,0]
	v_pk_mul_f32 v[204:205], v[128:129], v[178:179] op_sel_hi:[1,0]
	v_pk_mul_f32 v[160:161], v[138:139], v[178:179] op_sel_hi:[1,0]
	v_pk_mul_f32 v[162:163], v[136:137], v[178:179] op_sel_hi:[1,0]
	v_max_f32_e32 v160, 0, v160
	v_mul_f32_e32 v206, v160, v160
	v_max_f32_e32 v160, 0, v202
	v_mul_f32_e32 v202, v160, v160
	v_max_f32_e32 v160, 0, v161
	v_max_f32_e32 v162, 0, v162
	v_max_f32_e32 v163, 0, v163
	v_mul_f32_e32 v161, v160, v160
	v_max_f32_e32 v160, 0, v203
	v_mul_f32_e32 v162, v162, v162
	v_max_f32_e32 v204, 0, v204
	v_mul_f32_e32 v163, v163, v163
	v_max_f32_e32 v205, 0, v205
	v_mul_f32_e32 v203, v160, v160
	v_cvt_pk_bf16_f32 v160, v162, v163
	v_cvt_pk_bf16_f32 v161, v206, v161
	v_mul_f32_e32 v204, v204, v204
	v_mul_f32_e32 v205, v205, v205
	v_cvt_pk_bf16_f32 v162, v204, v205
	v_cvt_pk_bf16_f32 v163, v202, v203
	global_store_dwordx4 v164, v[160:163], s[0:1] offset:1024
	v_pk_mul_f32 v[202:203], v[134:135], v[178:179] op_sel_hi:[1,0]
	v_pk_mul_f32 v[204:205], v[132:133], v[178:179] op_sel_hi:[1,0]
	v_pk_mul_f32 v[160:161], v[142:143], v[178:179] op_sel_hi:[1,0]
	v_pk_mul_f32 v[162:163], v[140:141], v[178:179] op_sel_hi:[1,0]
	v_max_f32_e32 v160, 0, v160
	v_mul_f32_e32 v206, v160, v160
	v_max_f32_e32 v160, 0, v202
	v_mul_f32_e32 v202, v160, v160
	v_max_f32_e32 v160, 0, v161
	v_max_f32_e32 v162, 0, v162
	v_max_f32_e32 v163, 0, v163
	v_mul_f32_e32 v161, v160, v160
	v_max_f32_e32 v160, 0, v203
	v_mul_f32_e32 v162, v162, v162
	v_max_f32_e32 v204, 0, v204
	v_mul_f32_e32 v163, v163, v163
	v_max_f32_e32 v205, 0, v205
	v_mul_f32_e32 v203, v160, v160
	v_cvt_pk_bf16_f32 v160, v162, v163
	v_cvt_pk_bf16_f32 v161, v206, v161
	v_mul_f32_e32 v204, v204, v204
	v_mul_f32_e32 v205, v205, v205
	v_cvt_pk_bf16_f32 v162, v204, v205
	v_cvt_pk_bf16_f32 v163, v202, v203
	global_store_dwordx4 v[200:201], v[160:163], off offset:1024
	v_pk_mul_f32 v[202:203], v[114:115], v[176:177] op_sel_hi:[1,0]
	v_pk_mul_f32 v[204:205], v[112:113], v[176:177] op_sel_hi:[1,0]
	v_pk_mul_f32 v[160:161], v[122:123], v[176:177] op_sel_hi:[1,0]
	v_pk_mul_f32 v[162:163], v[120:121], v[176:177] op_sel_hi:[1,0]
	v_max_f32_e32 v160, 0, v160
	v_mul_f32_e32 v206, v160, v160
	v_max_f32_e32 v160, 0, v202
	v_mul_f32_e32 v202, v160, v160
	v_max_f32_e32 v160, 0, v161
	v_max_f32_e32 v162, 0, v162
	v_max_f32_e32 v163, 0, v163
	v_mul_f32_e32 v161, v160, v160
	v_max_f32_e32 v160, 0, v203
	v_mul_f32_e32 v162, v162, v162
	v_max_f32_e32 v204, 0, v204
	v_mul_f32_e32 v163, v163, v163
	v_max_f32_e32 v205, 0, v205
	v_mul_f32_e32 v203, v160, v160
	v_cvt_pk_bf16_f32 v160, v162, v163
	v_cvt_pk_bf16_f32 v161, v206, v161
	v_mul_f32_e32 v204, v204, v204
	v_mul_f32_e32 v205, v205, v205
	v_cvt_pk_bf16_f32 v162, v204, v205
	v_cvt_pk_bf16_f32 v163, v202, v203
	global_store_dwordx4 v164, v[160:163], s[0:1] offset:2048
	v_pk_mul_f32 v[202:203], v[118:119], v[176:177] op_sel_hi:[1,0]
	v_pk_mul_f32 v[204:205], v[116:117], v[176:177] op_sel_hi:[1,0]
	v_pk_mul_f32 v[160:161], v[126:127], v[176:177] op_sel_hi:[1,0]
	v_pk_mul_f32 v[162:163], v[124:125], v[176:177] op_sel_hi:[1,0]
	v_max_f32_e32 v160, 0, v160
	v_mul_f32_e32 v206, v160, v160
	v_max_f32_e32 v160, 0, v202
	v_mul_f32_e32 v202, v160, v160
	v_max_f32_e32 v160, 0, v161
	v_max_f32_e32 v162, 0, v162
	v_max_f32_e32 v163, 0, v163
	v_mul_f32_e32 v161, v160, v160
	v_max_f32_e32 v160, 0, v203
	v_mul_f32_e32 v162, v162, v162
	v_max_f32_e32 v204, 0, v204
	v_mul_f32_e32 v163, v163, v163
	v_max_f32_e32 v205, 0, v205
	v_mul_f32_e32 v203, v160, v160
	v_cvt_pk_bf16_f32 v160, v162, v163
	v_cvt_pk_bf16_f32 v161, v206, v161
	v_mul_f32_e32 v204, v204, v204
	v_mul_f32_e32 v205, v205, v205
	v_cvt_pk_bf16_f32 v162, v204, v205
	v_cvt_pk_bf16_f32 v163, v202, v203
	global_store_dwordx4 v[200:201], v[160:163], off offset:2048
	v_pk_mul_f32 v[200:201], v[98:99], v[174:175] op_sel_hi:[1,0]
	v_pk_mul_f32 v[202:203], v[96:97], v[174:175] op_sel_hi:[1,0]
	v_pk_mul_f32 v[160:161], v[106:107], v[174:175] op_sel_hi:[1,0]
	v_pk_mul_f32 v[162:163], v[104:105], v[174:175] op_sel_hi:[1,0]
	v_max_f32_e32 v160, 0, v160
	v_mul_f32_e32 v204, v160, v160
	v_max_f32_e32 v160, 0, v200
	v_mul_f32_e32 v200, v160, v160
	v_max_f32_e32 v160, 0, v161
	v_max_f32_e32 v162, 0, v162
	v_max_f32_e32 v163, 0, v163
	v_mul_f32_e32 v161, v160, v160
	v_max_f32_e32 v160, 0, v201
	v_mul_f32_e32 v162, v162, v162
	v_max_f32_e32 v202, 0, v202
	v_mul_f32_e32 v163, v163, v163
	v_max_f32_e32 v203, 0, v203
	v_mul_f32_e32 v201, v160, v160
	v_cvt_pk_bf16_f32 v160, v162, v163
	v_cvt_pk_bf16_f32 v161, v204, v161
	v_mul_f32_e32 v202, v202, v202
	v_mul_f32_e32 v203, v203, v203
	v_cvt_pk_bf16_f32 v162, v202, v203
	v_cvt_pk_bf16_f32 v163, v200, v201
	global_store_dwordx4 v164, v[160:163], s[0:1] offset:3072
	v_pk_mul_f32 v[200:201], v[102:103], v[174:175] op_sel_hi:[1,0]
	v_pk_mul_f32 v[202:203], v[100:101], v[174:175] op_sel_hi:[1,0]
	v_pk_mul_f32 v[160:161], v[110:111], v[174:175] op_sel_hi:[1,0]
	v_pk_mul_f32 v[162:163], v[108:109], v[174:175] op_sel_hi:[1,0]
	v_max_f32_e32 v160, 0, v160
	v_mul_f32_e32 v204, v160, v160
	v_max_f32_e32 v160, 0, v200
	v_max_f32_e32 v162, 0, v162
	v_max_f32_e32 v163, 0, v163
	v_mul_f32_e32 v200, v160, v160
	v_max_f32_e32 v160, 0, v161
	v_mul_f32_e32 v162, v162, v162
	v_max_f32_e32 v202, 0, v202
	v_mul_f32_e32 v163, v163, v163
	v_max_f32_e32 v203, 0, v203
	v_mul_f32_e32 v161, v160, v160
	v_max_f32_e32 v160, 0, v201
	v_mul_f32_e32 v202, v202, v202
	v_mul_f32_e32 v203, v203, v203
	v_mul_f32_e32 v201, v160, v160
	v_cvt_pk_bf16_f32 v160, v162, v163
	v_cvt_pk_bf16_f32 v161, v204, v161
	v_cvt_pk_bf16_f32 v162, v202, v203
	v_cvt_pk_bf16_f32 v163, v200, v201
	v_add_u32_e32 v164, 0x80c00, v164
	s_cbranch_execnz .LBB0_238

.LBB0_521:
	ds_read_b128 v[140:143], v138
	ds_read_b128 v[144:147], v138 offset:1024
	ds_read_b128 v[148:151], v138 offset:2048
	ds_read_b128 v[152:155], v138 offset:3072
	ds_read_b128 v[156:159], v193
	ds_read_b128 v[160:163], v193 offset:1024
	ds_read_b128 v[194:197], v192
	ds_read_b128 v[198:201], v192 offset:1024
	ds_read_b128 v[202:205], v191
	ds_read_b128 v[206:209], v191 offset:1024
	ds_read_b128 v[210:213], v190
	ds_read_b128 v[214:217], v190 offset:1024
	s_waitcnt lgkmcnt(8)
	s_waitcnt vmcnt(10)
	s_barrier
	s_waitcnt lgkmcnt(0)
	s_setprio 1
	s_waitcnt lgkmcnt(0)
	v_mfma_f32_16x16x32_bf16 v[124:127], v[140:143], v[156:159], v[124:127]
	v_mfma_f32_16x16x32_bf16 v[120:123], v[148:151], v[156:159], v[120:123]
	v_mfma_f32_16x16x32_bf16 v[116:119], v[140:143], v[194:197], v[116:119]
	v_mfma_f32_16x16x32_bf16 v[112:115], v[148:151], v[194:197], v[112:115]
	v_mfma_f32_16x16x32_bf16 v[108:111], v[140:143], v[202:205], v[108:111]
	v_mfma_f32_16x16x32_bf16 v[104:107], v[148:151], v[202:205], v[104:107]
	v_mfma_f32_16x16x32_bf16 v[100:103], v[140:143], v[210:213], v[100:103]
	v_mfma_f32_16x16x32_bf16 v[96:99], v[148:151], v[210:213], v[96:99]
	v_mfma_f32_16x16x32_bf16 v[124:127], v[144:147], v[160:163], v[124:127]
	v_mfma_f32_16x16x32_bf16 v[120:123], v[152:155], v[160:163], v[120:123]
	v_mfma_f32_16x16x32_bf16 v[116:119], v[144:147], v[198:201], v[116:119]
	v_mfma_f32_16x16x32_bf16 v[112:115], v[152:155], v[198:201], v[112:115]
	v_mfma_f32_16x16x32_bf16 v[108:111], v[144:147], v[206:209], v[108:111]
	v_mfma_f32_16x16x32_bf16 v[104:107], v[152:155], v[206:209], v[104:107]
	v_mfma_f32_16x16x32_bf16 v[100:103], v[144:147], v[214:217], v[100:103]
	v_mfma_f32_16x16x32_bf16 v[96:99], v[152:155], v[214:217], v[96:99]
	s_setprio 0
	s_barrier
	v_readfirstlane_b32 s36, v189
	v_lshl_add_u64 v[234:235], s[58:59], 0, v[164:165]
	s_mov_b32 m0, s36
	v_readfirstlane_b32 s36, v188
	ds_read_b128 v[218:221], v135
	ds_read_b128 v[222:225], v135 offset:1024
	ds_read_b128 v[226:229], v135 offset:2048
	ds_read_b128 v[230:233], v135 offset:3072
	global_load_lds_dwordx4 v[234:235], off
	v_lshl_add_u64 v[236:237], v[234:235], 0, s[2:3]
	s_mov_b32 m0, s36
	s_nop 0
	global_load_lds_dwordx4 v[236:237], off
	v_readfirstlane_b32 s36, v169
	v_lshl_add_u64 v[236:237], v[128:129], 0, s[22:23]
	s_mov_b32 m0, s36
	v_readfirstlane_b32 s36, v187
	global_load_lds_dwordx4 v[236:237], off
	v_lshl_add_u64 v[236:237], v[128:129], 0, s[24:25]
	s_mov_b32 m0, s36
	s_nop 0
	global_load_lds_dwordx4 v[236:237], off
	s_waitcnt vmcnt(12)
	s_barrier
	s_waitcnt lgkmcnt(0)
	s_setprio 1
	s_waitcnt lgkmcnt(0)
	v_mfma_f32_16x16x32_bf16 v[92:95], v[218:221], v[156:159], v[92:95]
	v_mfma_f32_16x16x32_bf16 v[88:91], v[226:229], v[156:159], v[88:91]
	v_mfma_f32_16x16x32_bf16 v[84:87], v[218:221], v[194:197], v[84:87]
	v_mfma_f32_16x16x32_bf16 v[80:83], v[226:229], v[194:197], v[80:83]
	v_mfma_f32_16x16x32_bf16 v[76:79], v[218:221], v[202:205], v[76:79]
	v_mfma_f32_16x16x32_bf16 v[72:75], v[226:229], v[202:205], v[72:75]
	v_mfma_f32_16x16x32_bf16 v[68:71], v[218:221], v[210:213], v[68:71]
	v_mfma_f32_16x16x32_bf16 v[64:67], v[226:229], v[210:213], v[64:67]
	v_mfma_f32_16x16x32_bf16 v[92:95], v[222:225], v[160:163], v[92:95]
	v_mfma_f32_16x16x32_bf16 v[88:91], v[230:233], v[160:163], v[88:91]
	v_mfma_f32_16x16x32_bf16 v[84:87], v[222:225], v[198:201], v[84:87]
	v_mfma_f32_16x16x32_bf16 v[80:83], v[230:233], v[198:201], v[80:83]
	v_mfma_f32_16x16x32_bf16 v[76:79], v[222:225], v[206:209], v[76:79]
	v_mfma_f32_16x16x32_bf16 v[72:75], v[230:233], v[206:209], v[72:75]
	v_mfma_f32_16x16x32_bf16 v[68:71], v[222:225], v[214:217], v[68:71]
	v_mfma_f32_16x16x32_bf16 v[64:67], v[230:233], v[214:217], v[64:67]
	s_setprio 0
	s_barrier
	ds_read_b128 v[156:159], v193 offset:16384
	ds_read_b128 v[160:163], v193 offset:17408
	ds_read_b128 v[194:197], v192 offset:16384
	ds_read_b128 v[198:201], v192 offset:17408
	ds_read_b128 v[202:205], v191 offset:16384
	ds_read_b128 v[206:209], v191 offset:17408
	ds_read_b128 v[210:213], v190 offset:16384
	ds_read_b128 v[214:217], v190 offset:17408
	v_readfirstlane_b32 s36, v186
	v_lshl_add_u64 v[236:237], v[234:235], 0, s[6:7]
	s_mov_b32 m0, s36
	v_readfirstlane_b32 s36, v185
	global_load_lds_dwordx4 v[236:237], off
	v_lshl_add_u64 v[236:237], v[234:235], 0, s[8:9]
	s_mov_b32 m0, s36
	s_nop 0
	global_load_lds_dwordx4 v[236:237], off
	s_barrier
	s_waitcnt lgkmcnt(0)
	s_setprio 1
	s_waitcnt lgkmcnt(0)
	v_mfma_f32_16x16x32_bf16 v[60:63], v[140:143], v[156:159], v[60:63]
	v_mfma_f32_16x16x32_bf16 v[56:59], v[148:151], v[156:159], v[56:59]
	v_mfma_f32_16x16x32_bf16 v[52:55], v[140:143], v[194:197], v[52:55]
	v_mfma_f32_16x16x32_bf16 v[48:51], v[148:151], v[194:197], v[48:51]
	v_mfma_f32_16x16x32_bf16 v[44:47], v[140:143], v[202:205], v[44:47]
	v_mfma_f32_16x16x32_bf16 v[40:43], v[148:151], v[202:205], v[40:43]
	v_mfma_f32_16x16x32_bf16 v[36:39], v[140:143], v[210:213], v[36:39]
	v_mfma_f32_16x16x32_bf16 v[32:35], v[148:151], v[210:213], v[32:35]
	v_mfma_f32_16x16x32_bf16 v[60:63], v[144:147], v[160:163], v[60:63]
	v_mfma_f32_16x16x32_bf16 v[56:59], v[152:155], v[160:163], v[56:59]
	v_mfma_f32_16x16x32_bf16 v[52:55], v[144:147], v[198:201], v[52:55]
	v_mfma_f32_16x16x32_bf16 v[48:51], v[152:155], v[198:201], v[48:51]
	v_mfma_f32_16x16x32_bf16 v[44:47], v[144:147], v[206:209], v[44:47]
	v_mfma_f32_16x16x32_bf16 v[40:43], v[152:155], v[206:209], v[40:43]
	v_mfma_f32_16x16x32_bf16 v[36:39], v[144:147], v[214:217], v[36:39]
	v_mfma_f32_16x16x32_bf16 v[32:35], v[152:155], v[214:217], v[32:35]
	s_setprio 0
	s_barrier
	v_readfirstlane_b32 s36, v184
	v_lshl_add_u64 v[142:143], v[128:129], 0, s[26:27]
	s_mov_b32 m0, s36
	v_readfirstlane_b32 s36, v183
	global_load_lds_dwordx4 v[142:143], off
	s_mov_b32 m0, s36
	s_nop 0
	global_load_lds_dwordx4 v[128:129], off
	s_waitcnt vmcnt(12)
	s_barrier
	s_setprio 1
	v_mfma_f32_16x16x32_bf16 v[28:31], v[218:221], v[156:159], v[28:31]
	v_mfma_f32_16x16x32_bf16 v[24:27], v[226:229], v[156:159], v[24:27]
	v_mfma_f32_16x16x32_bf16 v[20:23], v[218:221], v[194:197], v[20:23]
	v_mfma_f32_16x16x32_bf16 v[16:19], v[226:229], v[194:197], v[16:19]
	v_mfma_f32_16x16x32_bf16 v[12:15], v[218:221], v[202:205], v[12:15]
	v_mfma_f32_16x16x32_bf16 v[8:11], v[226:229], v[202:205], v[8:11]
	v_mfma_f32_16x16x32_bf16 v[4:7], v[218:221], v[210:213], v[4:7]
	v_mfma_f32_16x16x32_bf16 v[0:3], v[226:229], v[210:213], v[0:3]
	v_mfma_f32_16x16x32_bf16 v[28:31], v[222:225], v[160:163], v[28:31]
	v_mfma_f32_16x16x32_bf16 v[24:27], v[230:233], v[160:163], v[24:27]
	v_mfma_f32_16x16x32_bf16 v[20:23], v[222:225], v[198:201], v[20:23]
	v_mfma_f32_16x16x32_bf16 v[16:19], v[230:233], v[198:201], v[16:19]
	v_mfma_f32_16x16x32_bf16 v[12:15], v[222:225], v[206:209], v[12:15]
	v_mfma_f32_16x16x32_bf16 v[8:11], v[230:233], v[206:209], v[8:11]
	v_mfma_f32_16x16x32_bf16 v[4:7], v[222:225], v[214:217], v[4:7]
	v_mfma_f32_16x16x32_bf16 v[0:3], v[230:233], v[214:217], v[0:3]
	s_setprio 0
	s_barrier
	ds_read_b128 v[140:143], v130
	ds_read_b128 v[144:147], v130 offset:1024
	ds_read_b128 v[148:151], v130 offset:2048
	ds_read_b128 v[152:155], v130 offset:3072
	ds_read_b128 v[156:159], v193 offset:32768
	ds_read_b128 v[160:163], v193 offset:33792
	ds_read_b128 v[194:197], v192 offset:32768
	ds_read_b128 v[198:201], v192 offset:33792
	ds_read_b128 v[202:205], v191 offset:32768
	ds_read_b128 v[206:209], v191 offset:33792
	ds_read_b128 v[210:213], v190 offset:32768
	ds_read_b128 v[214:217], v190 offset:33792
	s_waitcnt lgkmcnt(8)
	s_waitcnt vmcnt(10)
	s_barrier
	s_waitcnt lgkmcnt(0)
	s_setprio 1
	s_waitcnt lgkmcnt(0)
	v_mfma_f32_16x16x32_bf16 v[124:127], v[140:143], v[156:159], v[124:127]
	v_mfma_f32_16x16x32_bf16 v[120:123], v[148:151], v[156:159], v[120:123]
	v_mfma_f32_16x16x32_bf16 v[116:119], v[140:143], v[194:197], v[116:119]
	v_mfma_f32_16x16x32_bf16 v[112:115], v[148:151], v[194:197], v[112:115]
	v_mfma_f32_16x16x32_bf16 v[108:111], v[140:143], v[202:205], v[108:111]
	v_mfma_f32_16x16x32_bf16 v[104:107], v[148:151], v[202:205], v[104:107]
	v_mfma_f32_16x16x32_bf16 v[100:103], v[140:143], v[210:213], v[100:103]
	v_mfma_f32_16x16x32_bf16 v[96:99], v[148:151], v[210:213], v[96:99]
	v_mfma_f32_16x16x32_bf16 v[124:127], v[144:147], v[160:163], v[124:127]
	v_mfma_f32_16x16x32_bf16 v[120:123], v[152:155], v[160:163], v[120:123]
	v_mfma_f32_16x16x32_bf16 v[116:119], v[144:147], v[198:201], v[116:119]
	v_mfma_f32_16x16x32_bf16 v[112:115], v[152:155], v[198:201], v[112:115]
	v_mfma_f32_16x16x32_bf16 v[108:111], v[144:147], v[206:209], v[108:111]
	v_mfma_f32_16x16x32_bf16 v[104:107], v[152:155], v[206:209], v[104:107]
	v_mfma_f32_16x16x32_bf16 v[100:103], v[144:147], v[214:217], v[100:103]
	v_mfma_f32_16x16x32_bf16 v[96:99], v[152:155], v[214:217], v[96:99]
	s_setprio 0
	s_barrier
	v_readfirstlane_b32 s36, v182
	v_lshl_add_u64 v[234:235], s[46:47], 0, v[164:165]
	s_mov_b32 m0, s36
	v_readfirstlane_b32 s36, v181
	ds_read_b128 v[218:221], v132
	ds_read_b128 v[222:225], v132 offset:1024
	ds_read_b128 v[226:229], v132 offset:2048
	ds_read_b128 v[230:233], v132 offset:3072
	global_load_lds_dwordx4 v[234:235], off
	v_lshl_add_u64 v[236:237], v[234:235], 0, s[2:3]
	s_mov_b32 m0, s36
	s_nop 0
	global_load_lds_dwordx4 v[236:237], off
	v_readfirstlane_b32 s36, v177
	v_lshl_add_u64 v[236:237], v[128:129], 0, s[28:29]
	s_mov_b32 m0, s36
	v_readfirstlane_b32 s36, v175
	global_load_lds_dwordx4 v[236:237], off
	v_lshl_add_u64 v[236:237], v[128:129], 0, s[30:31]
	s_mov_b32 m0, s36
	s_nop 0
	global_load_lds_dwordx4 v[236:237], off
	s_waitcnt vmcnt(12)
	s_barrier
	s_waitcnt lgkmcnt(0)
	s_setprio 1
	s_waitcnt lgkmcnt(0)
	v_mfma_f32_16x16x32_bf16 v[92:95], v[218:221], v[156:159], v[92:95]
	v_mfma_f32_16x16x32_bf16 v[88:91], v[226:229], v[156:159], v[88:91]
	v_mfma_f32_16x16x32_bf16 v[84:87], v[218:221], v[194:197], v[84:87]
	v_mfma_f32_16x16x32_bf16 v[80:83], v[226:229], v[194:197], v[80:83]
	v_mfma_f32_16x16x32_bf16 v[76:79], v[218:221], v[202:205], v[76:79]
	v_mfma_f32_16x16x32_bf16 v[72:75], v[226:229], v[202:205], v[72:75]
	v_mfma_f32_16x16x32_bf16 v[68:71], v[218:221], v[210:213], v[68:71]
	v_mfma_f32_16x16x32_bf16 v[64:67], v[226:229], v[210:213], v[64:67]
	v_mfma_f32_16x16x32_bf16 v[92:95], v[222:225], v[160:163], v[92:95]
	v_mfma_f32_16x16x32_bf16 v[88:91], v[230:233], v[160:163], v[88:91]
	v_mfma_f32_16x16x32_bf16 v[84:87], v[222:225], v[198:201], v[84:87]
	v_mfma_f32_16x16x32_bf16 v[80:83], v[230:233], v[198:201], v[80:83]
	v_mfma_f32_16x16x32_bf16 v[76:79], v[222:225], v[206:209], v[76:79]
	v_mfma_f32_16x16x32_bf16 v[72:75], v[230:233], v[206:209], v[72:75]
	v_mfma_f32_16x16x32_bf16 v[68:71], v[222:225], v[214:217], v[68:71]
	v_mfma_f32_16x16x32_bf16 v[64:67], v[230:233], v[214:217], v[64:67]
	s_setprio 0
	s_barrier
	ds_read_b128 v[156:159], v193 offset:49152
	ds_read_b128 v[160:163], v193 offset:50176
	ds_read_b128 v[194:197], v192 offset:49152
	ds_read_b128 v[198:201], v192 offset:50176
	ds_read_b128 v[202:205], v191 offset:49152
	ds_read_b128 v[206:209], v191 offset:50176
	ds_read_b128 v[210:213], v190 offset:49152
	ds_read_b128 v[214:217], v190 offset:50176
	v_readfirstlane_b32 s36, v173
	v_lshl_add_u64 v[236:237], v[234:235], 0, s[6:7]
	s_mov_b32 m0, s36
	v_readfirstlane_b32 s36, v171
	global_load_lds_dwordx4 v[236:237], off
	v_lshl_add_u64 v[236:237], v[234:235], 0, s[8:9]
	s_mov_b32 m0, s36
	s_nop 0
	global_load_lds_dwordx4 v[236:237], off
	s_barrier
	s_waitcnt lgkmcnt(0)
	s_setprio 1
	s_waitcnt lgkmcnt(0)
	v_mfma_f32_16x16x32_bf16 v[60:63], v[140:143], v[156:159], v[60:63]
	v_mfma_f32_16x16x32_bf16 v[56:59], v[148:151], v[156:159], v[56:59]
	v_mfma_f32_16x16x32_bf16 v[52:55], v[140:143], v[194:197], v[52:55]
	v_mfma_f32_16x16x32_bf16 v[48:51], v[148:151], v[194:197], v[48:51]
	v_mfma_f32_16x16x32_bf16 v[44:47], v[140:143], v[202:205], v[44:47]
	v_mfma_f32_16x16x32_bf16 v[40:43], v[148:151], v[202:205], v[40:43]
	v_mfma_f32_16x16x32_bf16 v[36:39], v[140:143], v[210:213], v[36:39]
	v_mfma_f32_16x16x32_bf16 v[32:35], v[148:151], v[210:213], v[32:35]
	v_mfma_f32_16x16x32_bf16 v[60:63], v[144:147], v[160:163], v[60:63]
	v_mfma_f32_16x16x32_bf16 v[56:59], v[152:155], v[160:163], v[56:59]
	v_mfma_f32_16x16x32_bf16 v[52:55], v[144:147], v[198:201], v[52:55]
	v_mfma_f32_16x16x32_bf16 v[48:51], v[152:155], v[198:201], v[48:51]
	v_mfma_f32_16x16x32_bf16 v[44:47], v[144:147], v[206:209], v[44:47]
	v_mfma_f32_16x16x32_bf16 v[40:43], v[152:155], v[206:209], v[40:43]
	v_mfma_f32_16x16x32_bf16 v[36:39], v[144:147], v[214:217], v[36:39]
	v_mfma_f32_16x16x32_bf16 v[32:35], v[152:155], v[214:217], v[32:35]
	s_setprio 0
	s_barrier
	v_lshl_add_u64 v[128:129], v[128:129], 0, s[34:35]
	v_readfirstlane_b32 s36, v137
	v_lshl_add_u64 v[142:143], v[128:129], 0, s[18:19]
	s_mov_b32 m0, s36
	v_readfirstlane_b32 s36, v136
	global_load_lds_dwordx4 v[142:143], off
	v_lshl_add_u64 v[142:143], v[128:129], 0, s[20:21]
	s_mov_b32 m0, s36
	s_nop 0
	global_load_lds_dwordx4 v[142:143], off
	s_waitcnt vmcnt(12)
	s_barrier
	s_setprio 1
	v_mfma_f32_16x16x32_bf16 v[28:31], v[218:221], v[156:159], v[28:31]
	v_mfma_f32_16x16x32_bf16 v[24:27], v[226:229], v[156:159], v[24:27]
	v_mfma_f32_16x16x32_bf16 v[20:23], v[218:221], v[194:197], v[20:23]
	v_mfma_f32_16x16x32_bf16 v[16:19], v[226:229], v[194:197], v[16:19]
	v_mfma_f32_16x16x32_bf16 v[12:15], v[218:221], v[202:205], v[12:15]
	v_mfma_f32_16x16x32_bf16 v[8:11], v[226:229], v[202:205], v[8:11]
	v_mfma_f32_16x16x32_bf16 v[4:7], v[218:221], v[210:213], v[4:7]
	v_mfma_f32_16x16x32_bf16 v[0:3], v[226:229], v[210:213], v[0:3]
	v_mfma_f32_16x16x32_bf16 v[28:31], v[222:225], v[160:163], v[28:31]
	v_mfma_f32_16x16x32_bf16 v[24:27], v[230:233], v[160:163], v[24:27]
	v_mfma_f32_16x16x32_bf16 v[20:23], v[222:225], v[198:201], v[20:23]
	v_mfma_f32_16x16x32_bf16 v[16:19], v[230:233], v[198:201], v[16:19]
	v_mfma_f32_16x16x32_bf16 v[12:15], v[222:225], v[206:209], v[12:15]
	v_mfma_f32_16x16x32_bf16 v[8:11], v[230:233], v[206:209], v[8:11]
	v_mfma_f32_16x16x32_bf16 v[4:7], v[222:225], v[214:217], v[4:7]
	v_mfma_f32_16x16x32_bf16 v[0:3], v[230:233], v[214:217], v[0:3]
	s_setprio 0
	s_add_i32 s14, s14, 2
	s_add_u32 s46, s46, s56
	s_addc_u32 s47, s47, s57
	s_add_u32 s58, s58, s56
	s_addc_u32 s59, s59, s57
	s_cmp_lt_u32 s14, 28
	s_barrier
	s_cbranch_scc1 .LBB0_521
	s_lshl_b32 s14, s60, 3
	s_or_b32 s80, s61, s14
	s_lshl_b32 s46, s80, 8
	v_lshlrev_b32_e32 v128, 3, v131
	v_lshlrev_b32_e32 v129, 5, v131
	s_or_b32 s14, s46, 0x80
	v_and_b32_e32 v128, 0x7fff0, v128
	v_and_b32_e32 v129, 32, v129
	s_lshl_b64 s[56:57], s[14:15], 13
	v_add_u32_e32 v129, v129, v134
	v_add_lshl_u32 v128, v133, v128, 13
	s_add_u32 s56, s40, s56
	v_lshl_add_u32 v164, v129, 1, v128
	s_addc_u32 s57, s41, s57
	v_lshl_add_u64 v[128:129], s[56:57], 0, v[164:165]
	v_readfirstlane_b32 s14, v137
	ds_read_b128 v[140:143], v138
	ds_read_b128 v[144:147], v138 offset:1024
	ds_read_b128 v[148:151], v138 offset:2048
	ds_read_b128 v[152:155], v138 offset:3072
	ds_read_b128 v[156:159], v193
	ds_read_b128 v[160:163], v193 offset:1024
	ds_read_b128 v[194:197], v192
	ds_read_b128 v[198:201], v192 offset:1024
	ds_read_b128 v[202:205], v191
	ds_read_b128 v[206:209], v191 offset:1024
	ds_read_b128 v[210:213], v190
	ds_read_b128 v[214:217], v190 offset:1024
	v_lshl_add_u64 v[138:139], v[128:129], 0, s[38:39]
	s_mov_b32 m0, s14
	v_readfirstlane_b32 s14, v136
	global_load_lds_dwordx4 v[138:139], off
	v_lshl_add_u64 v[128:129], v[128:129], 0, s[44:45]
	s_mov_b32 m0, s14
	s_mov_b32 s47, s15
	global_load_lds_dwordx4 v[128:129], off
	s_mul_i32 s98, s76, s84
	s_add_i32 s98, s98, s33
	s_cmpk_lt_u32 s98, 0x400
	s_cbranch_scc0 .Lpf12_skip
	v_mbcnt_lo_u32_b32 v243, -1, 0
	v_mbcnt_hi_u32_b32 v243, -1, v243
	v_add_u32_e32 v243, s64, v243
	v_lshrrev_b32_e32 v244, 1, v243
	v_lshlrev_b32_e32 v244, 13, v244
	v_and_b32_e32 v245, 1, v243
	v_lshl_or_b32 v244, v245, 7, v244
	v_lshrrev_b32_e32 v245, 7, v243
	v_lshlrev_b32_e32 v245, 19, v245
	v_and_b32_e32 v246, 0x7f, v243
	v_lshl_or_b32 v245, v246, 7, v245
	s_lshr_b32 s99, s98, 8
	s_lshl_b32 s99, s99, 11
	s_lshl_b32 s100, s98, 8
	s_and_b32 s100, s100, 0x700
	s_or_b32 s99, s99, s100
	s_lshl_b32 s99, s99, 13
	s_add_u32 s100, s40, s99
	s_addc_u32 s101, s41, 0
	global_load_dword v246, v244, s[100:101]
	s_and_b32 s98, s98, 0xf8
	s_lshl_b32 s98, s98, 11
	s_add_u32 s100, s62, s98
	s_addc_u32 s101, s63, 0
	global_load_dword v247, v245, s[100:101]
.Lpf12_skip:
	s_waitcnt vmcnt(12)
	s_barrier
	s_waitcnt lgkmcnt(0)
	s_setprio 1
	s_waitcnt lgkmcnt(0)
	v_mfma_f32_16x16x32_bf16 v[124:127], v[140:143], v[156:159], v[124:127]
	v_mfma_f32_16x16x32_bf16 v[120:123], v[148:151], v[156:159], v[120:123]
	v_mfma_f32_16x16x32_bf16 v[116:119], v[140:143], v[194:197], v[116:119]
	v_mfma_f32_16x16x32_bf16 v[112:115], v[148:151], v[194:197], v[112:115]
	v_mfma_f32_16x16x32_bf16 v[108:111], v[140:143], v[202:205], v[108:111]
	v_mfma_f32_16x16x32_bf16 v[104:107], v[148:151], v[202:205], v[104:107]
	v_mfma_f32_16x16x32_bf16 v[100:103], v[140:143], v[210:213], v[100:103]
	v_mfma_f32_16x16x32_bf16 v[96:99], v[148:151], v[210:213], v[96:99]
	v_mfma_f32_16x16x32_bf16 v[124:127], v[144:147], v[160:163], v[124:127]
	v_mfma_f32_16x16x32_bf16 v[120:123], v[152:155], v[160:163], v[120:123]
	v_mfma_f32_16x16x32_bf16 v[116:119], v[144:147], v[198:201], v[116:119]
	v_mfma_f32_16x16x32_bf16 v[112:115], v[152:155], v[198:201], v[112:115]
	v_mfma_f32_16x16x32_bf16 v[108:111], v[144:147], v[206:209], v[108:111]
	v_mfma_f32_16x16x32_bf16 v[104:107], v[152:155], v[206:209], v[104:107]
	v_mfma_f32_16x16x32_bf16 v[100:103], v[144:147], v[214:217], v[100:103]
	v_mfma_f32_16x16x32_bf16 v[96:99], v[152:155], v[214:217], v[96:99]
	s_setprio 0
	s_barrier
	ds_read_b128 v[136:139], v135
	ds_read_b128 v[218:221], v135 offset:1024
	ds_read_b128 v[222:225], v135 offset:2048
	ds_read_b128 v[226:229], v135 offset:3072
	s_barrier
	s_waitcnt lgkmcnt(0)
	s_setprio 1
	s_waitcnt lgkmcnt(0)
	v_mfma_f32_16x16x32_bf16 v[92:95], v[136:139], v[156:159], v[92:95]
	v_mfma_f32_16x16x32_bf16 v[84:87], v[136:139], v[194:197], v[84:87]
	v_mfma_f32_16x16x32_bf16 v[80:83], v[222:225], v[194:197], v[80:83]
	v_mfma_f32_16x16x32_bf16 v[88:91], v[222:225], v[156:159], v[88:91]
	v_mfma_f32_16x16x32_bf16 v[76:79], v[136:139], v[202:205], v[76:79]
	v_mfma_f32_16x16x32_bf16 v[72:75], v[222:225], v[202:205], v[72:75]
	v_mfma_f32_16x16x32_bf16 v[68:71], v[136:139], v[210:213], v[68:71]
	v_mfma_f32_16x16x32_bf16 v[64:67], v[222:225], v[210:213], v[64:67]
	v_mfma_f32_16x16x32_bf16 v[156:159], v[218:221], v[160:163], v[92:95]
	v_mfma_f32_16x16x32_bf16 v[194:197], v[218:221], v[198:201], v[84:87]
	v_mfma_f32_16x16x32_bf16 v[198:201], v[226:229], v[198:201], v[80:83]
	v_mfma_f32_16x16x32_bf16 v[160:163], v[226:229], v[160:163], v[88:91]
	v_mfma_f32_16x16x32_bf16 v[202:205], v[218:221], v[206:209], v[76:79]
	v_mfma_f32_16x16x32_bf16 v[206:209], v[226:229], v[206:209], v[72:75]
	v_mfma_f32_16x16x32_bf16 v[210:213], v[218:221], v[214:217], v[68:71]
	v_mfma_f32_16x16x32_bf16 v[214:217], v[226:229], v[214:217], v[64:67]
	s_setprio 0
	s_barrier
	s_nop 0
	ds_read_b128 v[64:67], v193 offset:16384
	ds_read_b128 v[68:71], v193 offset:17408
	ds_read_b128 v[72:75], v192 offset:16384
	ds_read_b128 v[76:79], v192 offset:17408
	ds_read_b128 v[80:83], v191 offset:16384
	ds_read_b128 v[84:87], v191 offset:17408
	ds_read_b128 v[88:91], v190 offset:16384
	ds_read_b128 v[92:95], v190 offset:17408
	s_waitcnt vmcnt(6)
	s_barrier
	s_waitcnt lgkmcnt(0)
	s_setprio 1
	s_waitcnt lgkmcnt(0)
	v_mfma_f32_16x16x32_bf16 v[60:63], v[140:143], v[64:67], v[60:63]
	v_mfma_f32_16x16x32_bf16 v[56:59], v[148:151], v[64:67], v[56:59]
	v_mfma_f32_16x16x32_bf16 v[52:55], v[140:143], v[72:75], v[52:55]
	v_mfma_f32_16x16x32_bf16 v[48:51], v[148:151], v[72:75], v[48:51]
	v_mfma_f32_16x16x32_bf16 v[230:233], v[140:143], v[80:83], v[44:47]
	v_mfma_f32_16x16x32_bf16 v[234:237], v[148:151], v[80:83], v[40:43]
	v_mfma_f32_16x16x32_bf16 v[140:143], v[140:143], v[88:91], v[36:39]
	v_mfma_f32_16x16x32_bf16 v[148:151], v[148:151], v[88:91], v[32:35]
	v_mfma_f32_16x16x32_bf16 v[32:35], v[144:147], v[68:71], v[60:63]
	v_mfma_f32_16x16x32_bf16 v[36:39], v[152:155], v[68:71], v[56:59]
	v_mfma_f32_16x16x32_bf16 v[40:43], v[144:147], v[76:79], v[52:55]
	v_mfma_f32_16x16x32_bf16 v[44:47], v[152:155], v[76:79], v[48:51]
	v_mfma_f32_16x16x32_bf16 v[48:51], v[144:147], v[84:87], v[230:233]
	v_mfma_f32_16x16x32_bf16 v[52:55], v[152:155], v[84:87], v[234:237]
	v_mfma_f32_16x16x32_bf16 v[56:59], v[144:147], v[92:95], v[140:143]
	v_mfma_f32_16x16x32_bf16 v[60:63], v[152:155], v[92:95], v[148:151]
	s_setprio 0
	s_setprio 1
	v_mfma_f32_16x16x32_bf16 v[28:31], v[136:139], v[64:67], v[28:31]
	v_mfma_f32_16x16x32_bf16 v[24:27], v[222:225], v[64:67], v[24:27]
	v_mfma_f32_16x16x32_bf16 v[20:23], v[136:139], v[72:75], v[20:23]
	v_mfma_f32_16x16x32_bf16 v[64:67], v[222:225], v[72:75], v[16:19]
	v_mfma_f32_16x16x32_bf16 v[12:15], v[136:139], v[80:83], v[12:15]
	v_mfma_f32_16x16x32_bf16 v[8:11], v[222:225], v[80:83], v[8:11]
	v_mfma_f32_16x16x32_bf16 v[72:75], v[136:139], v[88:91], v[4:7]
	v_mfma_f32_16x16x32_bf16 v[80:83], v[222:225], v[88:91], v[0:3]
	v_mfma_f32_16x16x32_bf16 v[0:3], v[218:221], v[68:71], v[28:31]
	v_mfma_f32_16x16x32_bf16 v[4:7], v[226:229], v[68:71], v[24:27]
	v_mfma_f32_16x16x32_bf16 v[16:19], v[218:221], v[76:79], v[20:23]
	v_mfma_f32_16x16x32_bf16 v[20:23], v[226:229], v[76:79], v[64:67]
	v_mfma_f32_16x16x32_bf16 v[24:27], v[218:221], v[84:87], v[12:15]
	v_mfma_f32_16x16x32_bf16 v[28:31], v[226:229], v[84:87], v[8:11]
	v_mfma_f32_16x16x32_bf16 v[64:67], v[218:221], v[92:95], v[72:75]
	v_mfma_f32_16x16x32_bf16 v[68:71], v[226:229], v[92:95], v[80:83]
	s_setprio 0
	s_barrier
	ds_read_b128 v[12:15], v130
	ds_read_b128 v[8:11], v130 offset:1024
	ds_read_b128 v[76:79], v130 offset:2048
	ds_read_b128 v[72:75], v130 offset:3072
	ds_read_b128 v[140:143], v193 offset:32768
	ds_read_b128 v[148:151], v193 offset:33792
	ds_read_b128 v[218:221], v192 offset:32768
	ds_read_b128 v[222:225], v192 offset:33792
	ds_read_b128 v[226:229], v191 offset:32768
	ds_read_b128 v[230:233], v191 offset:33792
	ds_read_b128 v[234:237], v190 offset:32768
	ds_read_b128 v[238:241], v190 offset:33792
	s_waitcnt vmcnt(4)
	s_barrier
	s_waitcnt lgkmcnt(0)
	s_setprio 1
	s_waitcnt lgkmcnt(0)
	v_mfma_f32_16x16x32_bf16 v[80:83], v[12:15], v[140:143], v[124:127]
	v_mfma_f32_16x16x32_bf16 v[84:87], v[76:79], v[140:143], v[120:123]
	v_mfma_f32_16x16x32_bf16 v[88:91], v[12:15], v[218:221], v[116:119]
	v_mfma_f32_16x16x32_bf16 v[92:95], v[76:79], v[218:221], v[112:115]
	v_mfma_f32_16x16x32_bf16 v[108:111], v[12:15], v[226:229], v[108:111]
	v_mfma_f32_16x16x32_bf16 v[104:107], v[76:79], v[226:229], v[104:107]
	v_mfma_f32_16x16x32_bf16 v[100:103], v[12:15], v[234:237], v[100:103]
	v_mfma_f32_16x16x32_bf16 v[96:99], v[76:79], v[234:237], v[96:99]
	v_mfma_f32_16x16x32_bf16 v[152:155], v[8:11], v[148:151], v[80:83]
	v_mfma_f32_16x16x32_bf16 v[144:147], v[72:75], v[148:151], v[84:87]
	v_mfma_f32_16x16x32_bf16 v[136:139], v[8:11], v[222:225], v[88:91]
	v_mfma_f32_16x16x32_bf16 v[128:131], v[72:75], v[222:225], v[92:95]
	v_mfma_f32_16x16x32_bf16 v[120:123], v[8:11], v[230:233], v[108:111]
	v_mfma_f32_16x16x32_bf16 v[112:115], v[72:75], v[230:233], v[104:107]
	v_mfma_f32_16x16x32_bf16 v[104:107], v[8:11], v[238:241], v[100:103]
	v_mfma_f32_16x16x32_bf16 v[96:99], v[72:75], v[238:241], v[96:99]
	s_setprio 0
	s_barrier
	ds_read_b128 v[88:91], v132
	ds_read_b128 v[80:83], v132 offset:1024
	ds_read_b128 v[92:95], v132 offset:2048
	ds_read_b128 v[84:87], v132 offset:3072
	s_waitcnt vmcnt(2)
	s_barrier
	s_waitcnt lgkmcnt(0)
	s_setprio 1
	s_waitcnt lgkmcnt(0)
	v_mfma_f32_16x16x32_bf16 v[100:103], v[88:91], v[140:143], v[156:159]
	v_mfma_f32_16x16x32_bf16 v[108:111], v[92:95], v[140:143], v[160:163]
	v_mfma_f32_16x16x32_bf16 v[116:119], v[88:91], v[218:221], v[194:197]
	v_mfma_f32_16x16x32_bf16 v[124:127], v[92:95], v[218:221], v[198:201]
	v_mfma_f32_16x16x32_bf16 v[160:163], v[88:91], v[226:229], v[202:205]
	v_mfma_f32_16x16x32_bf16 v[194:197], v[92:95], v[226:229], v[206:209]
	v_mfma_f32_16x16x32_bf16 v[198:201], v[88:91], v[234:237], v[210:213]
	v_mfma_f32_16x16x32_bf16 v[202:205], v[92:95], v[234:237], v[214:217]
	v_mfma_f32_16x16x32_bf16 v[156:159], v[80:83], v[148:151], v[100:103]
	v_mfma_f32_16x16x32_bf16 v[148:151], v[84:87], v[148:151], v[108:111]
	v_mfma_f32_16x16x32_bf16 v[140:143], v[80:83], v[222:225], v[116:119]
	v_mfma_f32_16x16x32_bf16 v[132:135], v[84:87], v[222:225], v[124:127]
	v_mfma_f32_16x16x32_bf16 v[124:127], v[80:83], v[230:233], v[160:163]
	v_mfma_f32_16x16x32_bf16 v[116:119], v[84:87], v[230:233], v[194:197]
	v_mfma_f32_16x16x32_bf16 v[108:111], v[80:83], v[238:241], v[198:201]
	v_mfma_f32_16x16x32_bf16 v[100:103], v[84:87], v[238:241], v[202:205]
	s_setprio 0
	s_lshl_b64 s[56:57], s[46:47], 2
	s_barrier
	v_mbcnt_lo_u32_b32 v162, -1, 0
	v_mbcnt_hi_u32_b32 v162, -1, v162
	s_add_u32 s56, s87, s56
	v_add_u32_e32 v160, s64, v162
	s_addc_u32 s57, s88, s57
	v_and_b32_e32 v164, 0x100, v160
	v_and_b32_e32 v162, 15, v162
	v_lshl_add_u64 v[160:161], s[56:57], 0, v[164:165]
	v_lshlrev_b32_e32 v164, 2, v162
	v_lshl_add_u64 v[160:161], v[160:161], 0, v[164:165]
	global_load_dword v180, v[160:161], off
	global_load_dword v178, v[160:161], off offset:64
	global_load_dword v176, v[160:161], off offset:128
	global_load_dword v174, v[160:161], off offset:192
	global_load_dword v172, v[160:161], off offset:512
	global_load_dword v170, v[160:161], off offset:576
	global_load_dword v168, v[160:161], off offset:640
	global_load_dword v166, v[160:161], off offset:704
	v_mbcnt_lo_u32_b32 v194, -1, 0
	v_mbcnt_hi_u32_b32 v194, -1, v194
	s_cmp_lg_u32 s79, 0
	v_add_u32_e32 v160, s64, v194
	v_bfe_u32 v196, v160, 8, 1
	v_ashrrev_i32_e32 v199, 6, v160
	v_bfe_u32 v160, v194, 4, 2
	s_cselect_b64 s[56:57], -1, 0
	v_and_b32_e32 v197, 3, v199
	v_and_b32_e32 v195, 15, v194
	s_and_b64 vcc, exec, s[56:57]
	v_lshlrev_b32_e32 v198, 4, v160
	s_cbranch_vccz .LBB0_533
	s_lshl_b32 s14, s78, 22
	s_lshl_b32 s36, s80, 14
	s_add_i32 s36, s36, s14
	v_lshlrev_b32_e32 v160, 6, v195
	v_or3_b32 v160, s36, v160, v198
	v_lshl_add_u32 v160, v197, 20, v160
	v_lshl_or_b32 v164, v196, 12, v160
	s_waitcnt vmcnt(0)
	v_pk_mul_f32 v[160:161], v[154:155], v[180:181] op_sel_hi:[1,0]
	v_pk_mul_f32 v[200:201], v[146:147], v[180:181] op_sel_hi:[1,0]
	v_max_f32_e32 v160, 0, v160
	v_mul_f32_e32 v204, v160, v160
	v_max_f32_e32 v160, 0, v200
	v_pk_mul_f32 v[162:163], v[152:153], v[180:181] op_sel_hi:[1,0]
	v_mul_f32_e32 v200, v160, v160
	v_max_f32_e32 v160, 0, v161
	v_pk_mul_f32 v[202:203], v[144:145], v[180:181] op_sel_hi:[1,0]
	v_max_f32_e32 v162, 0, v162
	v_max_f32_e32 v163, 0, v163
	v_mul_f32_e32 v161, v160, v160
	v_max_f32_e32 v160, 0, v201
	v_mul_f32_e32 v162, v162, v162
	v_max_f32_e32 v202, 0, v202
	v_mul_f32_e32 v163, v163, v163
	v_max_f32_e32 v203, 0, v203
	v_mul_f32_e32 v201, v160, v160
	v_cvt_pk_bf16_f32 v160, v162, v163
	v_cvt_pk_bf16_f32 v161, v204, v161
	v_mul_f32_e32 v202, v202, v202
	v_mul_f32_e32 v203, v203, v203
	v_cvt_pk_bf16_f32 v162, v202, v203
	v_cvt_pk_bf16_f32 v163, v200, v201
	global_store_dwordx4 v164, v[160:163], s[0:1]
	v_pk_mul_f32 v[202:203], v[150:151], v[180:181] op_sel_hi:[1,0]
	v_lshl_add_u64 v[200:201], s[0:1], 0, v[164:165]
	v_pk_mul_f32 v[160:161], v[158:159], v[180:181] op_sel_hi:[1,0]
	v_pk_mul_f32 v[162:163], v[156:157], v[180:181] op_sel_hi:[1,0]
	v_max_f32_e32 v160, 0, v160
	v_mul_f32_e32 v206, v160, v160
	v_max_f32_e32 v160, 0, v202
	v_mul_f32_e32 v202, v160, v160
	v_max_f32_e32 v160, 0, v161
	v_pk_mul_f32 v[204:205], v[148:149], v[180:181] op_sel_hi:[1,0]
	v_max_f32_e32 v162, 0, v162
	v_max_f32_e32 v163, 0, v163
	v_mul_f32_e32 v161, v160, v160
	v_max_f32_e32 v160, 0, v203
	v_add_co_u32_e32 v200, vcc, s72, v200
	v_mul_f32_e32 v162, v162, v162
	v_max_f32_e32 v204, 0, v204
	v_mul_f32_e32 v163, v163, v163
	v_max_f32_e32 v205, 0, v205
	v_mul_f32_e32 v203, v160, v160
	v_cvt_pk_bf16_f32 v160, v162, v163
	v_cvt_pk_bf16_f32 v161, v206, v161
	v_addc_co_u32_e32 v201, vcc, 0, v201, vcc
	v_mul_f32_e32 v204, v204, v204
	v_mul_f32_e32 v205, v205, v205
	v_cvt_pk_bf16_f32 v162, v204, v205
	v_cvt_pk_bf16_f32 v163, v202, v203
	global_store_dwordx4 v[200:201], v[160:163], off
	v_pk_mul_f32 v[202:203], v[130:131], v[178:179] op_sel_hi:[1,0]
	v_pk_mul_f32 v[204:205], v[128:129], v[178:179] op_sel_hi:[1,0]
	v_pk_mul_f32 v[160:161], v[138:139], v[178:179] op_sel_hi:[1,0]
	v_pk_mul_f32 v[162:163], v[136:137], v[178:179] op_sel_hi:[1,0]
	v_max_f32_e32 v160, 0, v160
	v_mul_f32_e32 v206, v160, v160
	v_max_f32_e32 v160, 0, v202
	v_mul_f32_e32 v202, v160, v160
	v_max_f32_e32 v160, 0, v161
	v_max_f32_e32 v162, 0, v162
	v_max_f32_e32 v163, 0, v163
	v_mul_f32_e32 v161, v160, v160
	v_max_f32_e32 v160, 0, v203
	v_mul_f32_e32 v162, v162, v162
	v_max_f32_e32 v204, 0, v204
	v_mul_f32_e32 v163, v163, v163
	v_max_f32_e32 v205, 0, v205
	v_mul_f32_e32 v203, v160, v160
	v_cvt_pk_bf16_f32 v160, v162, v163
	v_cvt_pk_bf16_f32 v161, v206, v161
	v_mul_f32_e32 v204, v204, v204
	v_mul_f32_e32 v205, v205, v205
	v_cvt_pk_bf16_f32 v162, v204, v205
	v_cvt_pk_bf16_f32 v163, v202, v203
	global_store_dwordx4 v164, v[160:163], s[0:1] offset:1024
	v_pk_mul_f32 v[202:203], v[134:135], v[178:179] op_sel_hi:[1,0]
	v_pk_mul_f32 v[204:205], v[132:133], v[178:179] op_sel_hi:[1,0]
	v_pk_mul_f32 v[160:161], v[142:143], v[178:179] op_sel_hi:[1,0]
	v_pk_mul_f32 v[162:163], v[140:141], v[178:179] op_sel_hi:[1,0]
	v_max_f32_e32 v160, 0, v160
	v_mul_f32_e32 v206, v160, v160
	v_max_f32_e32 v160, 0, v202
	v_mul_f32_e32 v202, v160, v160
	v_max_f32_e32 v160, 0, v161
	v_max_f32_e32 v162, 0, v162
	v_max_f32_e32 v163, 0, v163
	v_mul_f32_e32 v161, v160, v160
	v_max_f32_e32 v160, 0, v203
	v_mul_f32_e32 v162, v162, v162
	v_max_f32_e32 v204, 0, v204
	v_mul_f32_e32 v163, v163, v163
	v_max_f32_e32 v205, 0, v205
	v_mul_f32_e32 v203, v160, v160
	v_cvt_pk_bf16_f32 v160, v162, v163
	v_cvt_pk_bf16_f32 v161, v206, v161
	v_mul_f32_e32 v204, v204, v204
	v_mul_f32_e32 v205, v205, v205
	v_cvt_pk_bf16_f32 v162, v204, v205
	v_cvt_pk_bf16_f32 v163, v202, v203
	global_store_dwordx4 v[200:201], v[160:163], off offset:1024
	v_pk_mul_f32 v[202:203], v[114:115], v[176:177] op_sel_hi:[1,0]
	v_pk_mul_f32 v[204:205], v[112:113], v[176:177] op_sel_hi:[1,0]
	v_pk_mul_f32 v[160:161], v[122:123], v[176:177] op_sel_hi:[1,0]
	v_pk_mul_f32 v[162:163], v[120:121], v[176:177] op_sel_hi:[1,0]
	v_max_f32_e32 v160, 0, v160
	v_mul_f32_e32 v206, v160, v160
	v_max_f32_e32 v160, 0, v202
	v_mul_f32_e32 v202, v160, v160
	v_max_f32_e32 v160, 0, v161
	v_max_f32_e32 v162, 0, v162
	v_max_f32_e32 v163, 0, v163
	v_mul_f32_e32 v161, v160, v160
	v_max_f32_e32 v160, 0, v203
	v_mul_f32_e32 v162, v162, v162
	v_max_f32_e32 v204, 0, v204
	v_mul_f32_e32 v163, v163, v163
	v_max_f32_e32 v205, 0, v205
	v_mul_f32_e32 v203, v160, v160
	v_cvt_pk_bf16_f32 v160, v162, v163
	v_cvt_pk_bf16_f32 v161, v206, v161
	v_mul_f32_e32 v204, v204, v204
	v_mul_f32_e32 v205, v205, v205
	v_cvt_pk_bf16_f32 v162, v204, v205
	v_cvt_pk_bf16_f32 v163, v202, v203
	global_store_dwordx4 v164, v[160:163], s[0:1] offset:2048
	v_pk_mul_f32 v[202:203], v[118:119], v[176:177] op_sel_hi:[1,0]
	v_pk_mul_f32 v[204:205], v[116:117], v[176:177] op_sel_hi:[1,0]
	v_pk_mul_f32 v[160:161], v[126:127], v[176:177] op_sel_hi:[1,0]
	v_pk_mul_f32 v[162:163], v[124:125], v[176:177] op_sel_hi:[1,0]
	v_max_f32_e32 v160, 0, v160
	v_mul_f32_e32 v206, v160, v160
	v_max_f32_e32 v160, 0, v202
	v_mul_f32_e32 v202, v160, v160
	v_max_f32_e32 v160, 0, v161
	v_max_f32_e32 v162, 0, v162
	v_max_f32_e32 v163, 0, v163
	v_mul_f32_e32 v161, v160, v160
	v_max_f32_e32 v160, 0, v203
	v_mul_f32_e32 v162, v162, v162
	v_max_f32_e32 v204, 0, v204
	v_mul_f32_e32 v163, v163, v163
	v_max_f32_e32 v205, 0, v205
	v_mul_f32_e32 v203, v160, v160
	v_cvt_pk_bf16_f32 v160, v162, v163
	v_cvt_pk_bf16_f32 v161, v206, v161
	v_mul_f32_e32 v204, v204, v204
	v_mul_f32_e32 v205, v205, v205
	v_cvt_pk_bf16_f32 v162, v204, v205
	v_cvt_pk_bf16_f32 v163, v202, v203
	global_store_dwordx4 v[200:201], v[160:163], off offset:2048
	v_pk_mul_f32 v[200:201], v[98:99], v[174:175] op_sel_hi:[1,0]
	v_pk_mul_f32 v[202:203], v[96:97], v[174:175] op_sel_hi:[1,0]
	v_pk_mul_f32 v[160:161], v[106:107], v[174:175] op_sel_hi:[1,0]
	v_pk_mul_f32 v[162:163], v[104:105], v[174:175] op_sel_hi:[1,0]
	v_max_f32_e32 v160, 0, v160
	v_mul_f32_e32 v204, v160, v160
	v_max_f32_e32 v160, 0, v200
	v_mul_f32_e32 v200, v160, v160
	v_max_f32_e32 v160, 0, v161
	v_max_f32_e32 v162, 0, v162
	v_max_f32_e32 v163, 0, v163
	v_mul_f32_e32 v161, v160, v160
	v_max_f32_e32 v160, 0, v201
	v_mul_f32_e32 v162, v162, v162
	v_max_f32_e32 v202, 0, v202
	v_mul_f32_e32 v163, v163, v163
	v_max_f32_e32 v203, 0, v203
	v_mul_f32_e32 v201, v160, v160
	v_cvt_pk_bf16_f32 v160, v162, v163
	v_cvt_pk_bf16_f32 v161, v204, v161
	v_mul_f32_e32 v202, v202, v202
	v_mul_f32_e32 v203, v203, v203
	v_cvt_pk_bf16_f32 v162, v202, v203
	v_cvt_pk_bf16_f32 v163, v200, v201
	global_store_dwordx4 v164, v[160:163], s[0:1] offset:3072
	v_pk_mul_f32 v[200:201], v[102:103], v[174:175] op_sel_hi:[1,0]
	v_pk_mul_f32 v[202:203], v[100:101], v[174:175] op_sel_hi:[1,0]
	v_pk_mul_f32 v[160:161], v[110:111], v[174:175] op_sel_hi:[1,0]
	v_pk_mul_f32 v[162:163], v[108:109], v[174:175] op_sel_hi:[1,0]
	v_max_f32_e32 v160, 0, v160
	v_mul_f32_e32 v204, v160, v160
	v_max_f32_e32 v160, 0, v200
	v_max_f32_e32 v162, 0, v162
	v_max_f32_e32 v163, 0, v163
	v_mul_f32_e32 v200, v160, v160
	v_max_f32_e32 v160, 0, v161
	v_mul_f32_e32 v162, v162, v162
	v_max_f32_e32 v202, 0, v202
	v_mul_f32_e32 v163, v163, v163
	v_max_f32_e32 v203, 0, v203
	v_mul_f32_e32 v161, v160, v160
	v_max_f32_e32 v160, 0, v201
	v_mul_f32_e32 v202, v202, v202
	v_mul_f32_e32 v203, v203, v203
	v_mul_f32_e32 v201, v160, v160
	v_cvt_pk_bf16_f32 v160, v162, v163
	v_cvt_pk_bf16_f32 v161, v204, v161
	v_cvt_pk_bf16_f32 v162, v202, v203
	v_cvt_pk_bf16_f32 v163, v200, v201
	v_add_u32_e32 v164, 0x80c00, v164
	s_cbranch_execnz .LBB0_525

	.amdhsa_kernel _Z14fwd_megakernel6Params
		.amdhsa_group_segment_fixed_size 149504
		.amdhsa_private_segment_fixed_size 0
		.amdhsa_kernarg_size 392
		.amdhsa_user_sgpr_count 2
		.amdhsa_user_sgpr_dispatch_ptr 0
		.amdhsa_user_sgpr_queue_ptr 0
		.amdhsa_user_sgpr_kernarg_segment_ptr 1
		.amdhsa_user_sgpr_dispatch_id 0
		.amdhsa_user_sgpr_kernarg_preload_length 0
		.amdhsa_user_sgpr_kernarg_preload_offset 0
		.amdhsa_user_sgpr_private_segment_size 0
		.amdhsa_uses_dynamic_stack 0
		.amdhsa_enable_private_segment 0
		.amdhsa_system_sgpr_workgroup_id_x 1
		.amdhsa_system_sgpr_workgroup_id_y 0
		.amdhsa_system_sgpr_workgroup_id_z 0
		.amdhsa_system_sgpr_workgroup_info 0
		.amdhsa_system_vgpr_workitem_id 2
		.amdhsa_next_free_vgpr 256
		.amdhsa_next_free_sgpr 102
		.amdhsa_accum_offset 256
		.amdhsa_reserve_vcc 1
		.amdhsa_float_round_mode_32 0
		.amdhsa_float_round_mode_16_64 0
		.amdhsa_float_denorm_mode_32 3
		.amdhsa_float_denorm_mode_16_64 3
		.amdhsa_dx10_clamp 1
		.amdhsa_ieee_mode 1
		.amdhsa_fp16_overflow 0
		.amdhsa_tg_split 0
		.amdhsa_exception_fp_ieee_invalid_op 0
		.amdhsa_exception_fp_denorm_src 0
		.amdhsa_exception_fp_ieee_div_zero 0
		.amdhsa_exception_fp_ieee_overflow 0
		.amdhsa_exception_fp_ieee_underflow 0
		.amdhsa_exception_fp_ieee_inexact 0
		.amdhsa_exception_int_div_zero 0
	.end_amdhsa_kernel

amdhsa.kernels:
  - .agpr_count:     0
    .args:
      - .offset:         0
        .size:           136
        .value_kind:     by_value
      - .offset:         136
        .size:           4
        .value_kind:     hidden_block_count_x
      - .offset:         140
        .size:           4
        .value_kind:     hidden_block_count_y
      - .offset:         144
        .size:           4
        .value_kind:     hidden_block_count_z
      - .offset:         148
        .size:           2
        .value_kind:     hidden_group_size_x
      - .offset:         150
        .size:           2
        .value_kind:     hidden_group_size_y
      - .offset:         152
        .size:           2
        .value_kind:     hidden_group_size_z
      - .offset:         154
        .size:           2
        .value_kind:     hidden_remainder_x
      - .offset:         156
        .size:           2
        .value_kind:     hidden_remainder_y
      - .offset:         158
        .size:           2
        .value_kind:     hidden_remainder_z
      - .offset:         176
        .size:           8
        .value_kind:     hidden_global_offset_x
      - .offset:         184
        .size:           8
        .value_kind:     hidden_global_offset_y
      - .offset:         192
        .size:           8
        .value_kind:     hidden_global_offset_z
      - .offset:         200
        .size:           2
        .value_kind:     hidden_grid_dims
      - .offset:         224
        .size:           8
        .value_kind:     hidden_multigrid_sync_arg
    .group_segment_fixed_size: 149504
    .kernarg_segment_align: 8
    .kernarg_segment_size: 392
    .language:       OpenCL C
    .language_version:
      - 2
      - 0
    .max_flat_workgroup_size: 512
    .name:           _Z14fwd_megakernel6Params
    .private_segment_fixed_size: 0
    .sgpr_count:     108
    .sgpr_spill_count: 5
    .symbol:         _Z14fwd_megakernel6Params.kd
    .uniform_work_group_size: 1
    .uses_dynamic_stack: false
    .vgpr_count:     256
    .vgpr_spill_count: 0
    .wavefront_size: 64
